# GEMM K-loops: removed the momentary s_setprio 0/1 pair inside each 32-MFMA run and the already-satisfied lgkmcnt(0) after the segment barrier
# speedup vs baseline: 1.0188x; 1.0188x over previous
; #define PG8_STAGE(bufoff, gbase, voff) do { _Pragma("unroll") for (int _i = 0; _i < 2; ++_i) \
;         __builtin_amdgcn_global_load_lds((const unsigned*)((const char*)(gbase) + (voff)[_i]), (LAS unsigned*)(lds + (bufoff) + ldsw + _i * 8192), 16, 0, 0); } while (0)
; #define PG8_LDA(dst, b, h) do { _Pragma("unroll") for (int m = 0; m < 4; ++m) _Pragma("unroll") for (int k = 0; k < 2; ++k) dst[m][k] = *(const LAS bf16x8*)(lds + PG8_SA(b, h) + aoff + m * 2048 + k * 1024); } while (0)
; #define PG8_LDB(dst, b, h) do { _Pragma("unroll") for (int n = 0; n < 2; ++n) _Pragma("unroll") for (int k = 0; k < 2; ++k) dst[n][k] = *(const LAS bf16x8*)(lds + PG8_SB(b, h) + boff + n * 2048 + k * 1024); } while (0)
; #define PG8_MMA(ai, bj, At, Bt) do { __builtin_amdgcn_s_setprio(1); _Pragma("unroll") for (int m = 0; m < 4; ++m) _Pragma("unroll") for (int n = 0; n < 2; ++n) _Pragma("unroll") for (int k = 0; k < 2; ++k) \
;         acc[ai][bj][m][n] = __builtin_amdgcn_mfma_f32_16x16x32_bf16(Bt[n][k], At[m][k], acc[ai][bj][m][n], 0, 0, 0); __builtin_amdgcn_s_setprio(0); } while (0)
; #define PG8_WAIT_V(n) asm volatile("s_waitcnt vmcnt(" #n ")" ::: "memory")
; #define PG8_WAIT_L(n) asm volatile("s_waitcnt lgkmcnt(" #n ")" ::: "memory")
; #define PG8_BAR __builtin_amdgcn_s_barrier()
; #define PG8_SCHED __builtin_amdgcn_sched_barrier(0)
; template <bool ALIGN_EPI, class Epi, class Sched>
; DEV void gemm_phase(LAS unsigned char* lds, const Gemm g, const Sched& S, const Epi& E) {
;     ...
;         for (int t = 0; t < nt; t += 2) {
;             const bool last = (t == nt - 2);
;             const char* a1 = cA + (size_t)(t + 1) * kstep;
;             const char* a2 = last ? nA : cA + (size_t)(t + 2) * kstep; const char* b2 = last ? nB : cB + (size_t)(t + 2) * kstep;
;             const char* a3 = a2 + kstep; const char* b3 = b2 + kstep;
;             PG8_LDB(B0, 0, 0); PG8_LDB(B1, 0, 1); PG8_SCHED; PG8_LDA(At, 0, 0); PG8_STAGE(PG8_SA(1, 1), a1 + hstepA, voffA);
;             PG8_WAIT_V(8); PG8_WAIT_L(0); PG8_BAR; PG8_MMA(0, 0, At, B0); PG8_MMA(0, 1, At, B1); PG8_BAR; PG8_SCHED;
;             PG8_LDA(At, 0, 1); PG8_STAGE(PG8_SB(0, 0), b2, voffB); PG8_STAGE(PG8_SB(0, 1), b2 + hstep, voffB); PG8_STAGE(PG8_SA(0, 0), a2, voffA);
;             PG8_WAIT_V(8); PG8_WAIT_L(0); PG8_BAR; PG8_MMA(1, 0, At, B0); PG8_MMA(1, 1, At, B1); PG8_BAR; PG8_SCHED;
.LBB0_28:
	s_add_u32 s6, s4, 0x100
	s_addc_u32 s7, s5, 0
	s_add_i32 s24, 0, 0x10000
	s_cmp_eq_u32 s49, 12
	s_cselect_b32 s93, s85, s7
	s_cselect_b32 s92, vcc_lo, s6
	s_cselect_b32 s91, s83, s48
	s_cselect_b32 s90, vcc_hi, s21
	s_add_i32 s25, 0, 0x14000
	v_add_u32_e32 v82, s24, v171
	s_waitcnt lgkmcnt(0)
	v_add_u32_e32 v158, s25, v171
	ds_read_b128 v[62:65], v82
	ds_read_b128 v[66:69], v82 offset:1024
	ds_read_b128 v[78:81], v82 offset:2048
	ds_read_b128 v[82:85], v82 offset:3072
	ds_read_b128 v[122:125], v158
	ds_read_b128 v[134:137], v158 offset:1024
	ds_read_b128 v[154:157], v158 offset:2048
	ds_read_b128 v[158:161], v158 offset:3072
	v_lshl_add_u64 v[208:209], s[4:5], 0, v[188:189]
	s_add_i32 m0, s12, 0xc000
	ds_read_b128 v[162:165], v230
	ds_read_b128 v[166:169], v230 offset:1024
	ds_read_b128 v[192:195], v230 offset:2048
	ds_read_b128 v[196:199], v230 offset:3072
	ds_read_b128 v[200:203], v230 offset:4096
	ds_read_b128 v[204:207], v230 offset:5120
	ds_read_b128 v[232:235], v230 offset:6144
	ds_read_b128 v[236:239], v230 offset:7168
	global_load_lds_dwordx4 v[208:209], off
	v_lshl_add_u64 v[208:209], s[4:5], 0, v[190:191]
	s_add_i32 m0, s12, 0xe000
	s_nop 0
	global_load_lds_dwordx4 v[208:209], off
	s_waitcnt vmcnt(8)
	s_waitcnt lgkmcnt(0)
	s_barrier
	s_setprio 1
	v_mfma_f32_16x16x32_bf16 v[130:133], v[62:65], v[162:165], v[130:133]
	v_mfma_f32_16x16x32_bf16 v[118:121], v[78:81], v[162:165], v[118:121]
	v_mfma_f32_16x16x32_bf16 v[110:113], v[62:65], v[192:195], v[110:113]
	v_mfma_f32_16x16x32_bf16 v[102:105], v[78:81], v[192:195], v[102:105]
	v_mfma_f32_16x16x32_bf16 v[94:97], v[62:65], v[200:203], v[94:97]
	v_mfma_f32_16x16x32_bf16 v[86:89], v[78:81], v[200:203], v[86:89]
	v_mfma_f32_16x16x32_bf16 v[70:73], v[62:65], v[232:235], v[70:73]
	v_mfma_f32_16x16x32_bf16 v[54:57], v[78:81], v[232:235], v[54:57]
	v_mfma_f32_16x16x32_bf16 v[130:133], v[66:69], v[166:169], v[130:133]
	v_mfma_f32_16x16x32_bf16 v[118:121], v[82:85], v[166:169], v[118:121]
	v_mfma_f32_16x16x32_bf16 v[110:113], v[66:69], v[196:199], v[110:113]
	v_mfma_f32_16x16x32_bf16 v[102:105], v[82:85], v[196:199], v[102:105]
	v_mfma_f32_16x16x32_bf16 v[94:97], v[66:69], v[204:207], v[94:97]
	v_mfma_f32_16x16x32_bf16 v[86:89], v[82:85], v[204:207], v[86:89]
	v_mfma_f32_16x16x32_bf16 v[70:73], v[66:69], v[236:239], v[70:73]
	v_mfma_f32_16x16x32_bf16 v[54:57], v[82:85], v[236:239], v[54:57]
	v_mfma_f32_16x16x32_bf16 v[150:153], v[122:125], v[162:165], v[150:153]
	v_mfma_f32_16x16x32_bf16 v[146:149], v[154:157], v[162:165], v[146:149]
	v_mfma_f32_16x16x32_bf16 v[142:145], v[122:125], v[192:195], v[142:145]
	v_mfma_f32_16x16x32_bf16 v[138:141], v[154:157], v[192:195], v[138:141]
	v_mfma_f32_16x16x32_bf16 v[126:129], v[122:125], v[200:203], v[126:129]
	v_mfma_f32_16x16x32_bf16 v[114:117], v[154:157], v[200:203], v[114:117]
	v_mfma_f32_16x16x32_bf16 v[106:109], v[122:125], v[232:235], v[106:109]
	v_mfma_f32_16x16x32_bf16 v[98:101], v[154:157], v[232:235], v[98:101]
	v_mfma_f32_16x16x32_bf16 v[150:153], v[134:137], v[166:169], v[150:153]
	v_mfma_f32_16x16x32_bf16 v[146:149], v[158:161], v[166:169], v[146:149]
	v_mfma_f32_16x16x32_bf16 v[142:145], v[134:137], v[196:199], v[142:145]
	v_mfma_f32_16x16x32_bf16 v[138:141], v[158:161], v[196:199], v[138:141]
	v_mfma_f32_16x16x32_bf16 v[126:129], v[134:137], v[204:207], v[126:129]
	v_mfma_f32_16x16x32_bf16 v[114:117], v[158:161], v[204:207], v[114:117]
	v_mfma_f32_16x16x32_bf16 v[106:109], v[134:137], v[236:239], v[106:109]
	v_mfma_f32_16x16x32_bf16 v[98:101], v[158:161], v[236:239], v[98:101]
	s_setprio 0
	s_barrier
	s_add_i32 s4, s24, s8
	v_lshl_add_u64 v[208:209], s[90:91], 0, v[0:1]
	s_mov_b32 m0, s4
	ds_read_b128 v[162:165], v230 offset:16384
	ds_read_b128 v[166:169], v230 offset:17408
	ds_read_b128 v[192:195], v230 offset:18432
	ds_read_b128 v[196:199], v230 offset:19456
	ds_read_b128 v[200:203], v230 offset:20480
	ds_read_b128 v[204:207], v230 offset:21504
	ds_read_b128 v[232:235], v230 offset:22528
	ds_read_b128 v[236:239], v230 offset:23552
	global_load_lds_dwordx4 v[208:209], off
	s_add_i32 m0, s4, 0x2000
	s_add_u32 s4, s90, 0x40000
	v_lshl_add_u64 v[214:215], s[90:91], 0, v[180:181]
	s_addc_u32 s5, s91, 0
	s_add_i32 s24, s25, s8
	global_load_lds_dwordx4 v[214:215], off
	v_lshl_add_u64 v[240:241], s[4:5], 0, v[0:1]
	s_mov_b32 m0, s24
	v_lshl_add_u64 v[242:243], s[92:93], 0, v[182:183]
	global_load_lds_dwordx4 v[240:241], off
	v_lshl_add_u64 v[240:241], s[4:5], 0, v[180:181]
	s_add_i32 m0, s24, 0x2000
	s_nop 0
	global_load_lds_dwordx4 v[240:241], off
	v_lshl_add_u64 v[240:241], s[92:93], 0, v[184:185]
	s_mov_b32 m0, s12
	s_nop 0
	global_load_lds_dwordx4 v[240:241], off
	s_mov_b32 m0, s13
	s_nop 0
	global_load_lds_dwordx4 v[242:243], off
	s_waitcnt vmcnt(8)
	s_waitcnt lgkmcnt(0)
	s_barrier
; #define PG8_STAGE(bufoff, gbase, voff) do { _Pragma("unroll") for (int _i = 0; _i < 2; ++_i) \
;         __builtin_amdgcn_global_load_lds((const unsigned*)((const char*)(gbase) + (voff)[_i]), (LAS unsigned*)(lds + (bufoff) + ldsw + _i * 8192), 16, 0, 0); } while (0)
; #define PG8_LDA(dst, b, h) do { _Pragma("unroll") for (int m = 0; m < 4; ++m) _Pragma("unroll") for (int k = 0; k < 2; ++k) dst[m][k] = *(const LAS bf16x8*)(lds + PG8_SA(b, h) + aoff + m * 2048 + k * 1024); } while (0)
; #define PG8_LDB(dst, b, h) do { _Pragma("unroll") for (int n = 0; n < 2; ++n) _Pragma("unroll") for (int k = 0; k < 2; ++k) dst[n][k] = *(const LAS bf16x8*)(lds + PG8_SB(b, h) + boff + n * 2048 + k * 1024); } while (0)
; #define PG8_MMA(ai, bj, At, Bt) do { __builtin_amdgcn_s_setprio(1); _Pragma("unroll") for (int m = 0; m < 4; ++m) _Pragma("unroll") for (int n = 0; n < 2; ++n) _Pragma("unroll") for (int k = 0; k < 2; ++k) \
;         acc[ai][bj][m][n] = __builtin_amdgcn_mfma_f32_16x16x32_bf16(Bt[n][k], At[m][k], acc[ai][bj][m][n], 0, 0, 0); __builtin_amdgcn_s_setprio(0); } while (0)
; #define PG8_WAIT_V(n) asm volatile("s_waitcnt vmcnt(" #n ")" ::: "memory")
; #define PG8_WAIT_L(n) asm volatile("s_waitcnt lgkmcnt(" #n ")" ::: "memory")
; #define PG8_BAR __builtin_amdgcn_s_barrier()
; #define PG8_SCHED __builtin_amdgcn_sched_barrier(0)
; template <bool ALIGN_EPI, class Epi, class Sched>
; DEV void gemm_phase(LAS unsigned char* lds, const Gemm g, const Sched& S, const Epi& E) {
;     ...
;             PG8_WAIT_V(8); PG8_WAIT_L(0); PG8_BAR; PG8_MMA(1, 0, At, B0); PG8_MMA(1, 1, At, B1); PG8_BAR; PG8_SCHED;
;             PG8_LDB(B0, 1, 0); PG8_LDB(B1, 1, 1); PG8_SCHED; PG8_LDA(At, 1, 0); PG8_STAGE(PG8_SA(0, 1), a2 + hstepA, voffA);
;             PG8_WAIT_V(8); PG8_WAIT_L(0); PG8_BAR; PG8_MMA(0, 0, At, B0); PG8_MMA(0, 1, At, B1); PG8_BAR; PG8_SCHED;
	s_setprio 1
	v_mfma_f32_16x16x32_bf16 v[46:49], v[62:65], v[162:165], v[46:49]
	v_mfma_f32_16x16x32_bf16 v[38:41], v[78:81], v[162:165], v[38:41]
	v_mfma_f32_16x16x32_bf16 v[30:33], v[62:65], v[192:195], v[30:33]
	v_mfma_f32_16x16x32_bf16 v[14:17], v[78:81], v[192:195], v[14:17]
	v_mfma_f32_16x16x32_bf16 v[26:29], v[62:65], v[200:203], v[26:29]
	v_mfma_f32_16x16x32_bf16 v[10:13], v[78:81], v[200:203], v[10:13]
	v_mfma_f32_16x16x32_bf16 v[22:25], v[62:65], v[232:235], v[22:25]
	v_mfma_f32_16x16x32_bf16 v[6:9], v[78:81], v[232:235], v[6:9]
	v_mfma_f32_16x16x32_bf16 v[46:49], v[66:69], v[166:169], v[46:49]
	v_mfma_f32_16x16x32_bf16 v[38:41], v[82:85], v[166:169], v[38:41]
	v_mfma_f32_16x16x32_bf16 v[30:33], v[66:69], v[196:199], v[30:33]
	v_mfma_f32_16x16x32_bf16 v[14:17], v[82:85], v[196:199], v[14:17]
	v_mfma_f32_16x16x32_bf16 v[26:29], v[66:69], v[204:207], v[26:29]
	v_mfma_f32_16x16x32_bf16 v[10:13], v[82:85], v[204:207], v[10:13]
	v_mfma_f32_16x16x32_bf16 v[22:25], v[66:69], v[236:239], v[22:25]
	v_mfma_f32_16x16x32_bf16 v[6:9], v[82:85], v[236:239], v[6:9]
	v_mfma_f32_16x16x32_bf16 v[58:61], v[122:125], v[192:195], v[58:61]
	v_mfma_f32_16x16x32_bf16 v[50:53], v[154:157], v[192:195], v[50:53]
	v_mfma_f32_16x16x32_bf16 v[42:45], v[122:125], v[200:203], v[42:45]
	v_mfma_f32_16x16x32_bf16 v[34:37], v[154:157], v[200:203], v[34:37]
	v_mfma_f32_16x16x32_bf16 v[18:21], v[122:125], v[232:235], v[18:21]
	v_mfma_f32_16x16x32_bf16 v[2:5], v[154:157], v[232:235], v[2:5]
	v_mfma_f32_16x16x32_bf16 v[62:65], v[122:125], v[162:165], v[90:93]
	v_mfma_f32_16x16x32_bf16 v[66:69], v[154:157], v[162:165], v[74:77]
	v_mfma_f32_16x16x32_bf16 v[58:61], v[134:137], v[196:199], v[58:61]
	v_mfma_f32_16x16x32_bf16 v[50:53], v[158:161], v[196:199], v[50:53]
	v_mfma_f32_16x16x32_bf16 v[42:45], v[134:137], v[204:207], v[42:45]
	v_mfma_f32_16x16x32_bf16 v[34:37], v[158:161], v[204:207], v[34:37]
	v_mfma_f32_16x16x32_bf16 v[18:21], v[134:137], v[236:239], v[18:21]
	v_mfma_f32_16x16x32_bf16 v[2:5], v[158:161], v[236:239], v[2:5]
	v_mfma_f32_16x16x32_bf16 v[62:65], v[134:137], v[166:169], v[62:65]
	v_mfma_f32_16x16x32_bf16 v[66:69], v[158:161], v[166:169], v[66:69]
	s_setprio 0
	s_barrier
	s_add_i32 s24, 0, 0x18000
	s_add_i32 s25, 0, 0x1c000
	v_add_u32_e32 v90, s24, v171
	v_add_u32_e32 v158, s25, v171
	ds_read_b128 v[74:77], v90
	ds_read_b128 v[78:81], v90 offset:1024
	ds_read_b128 v[82:85], v90 offset:2048
	ds_read_b128 v[90:93], v90 offset:3072
	ds_read_b128 v[122:125], v158
	ds_read_b128 v[134:137], v158 offset:1024
	ds_read_b128 v[154:157], v158 offset:2048
	ds_read_b128 v[158:161], v158 offset:3072
	s_add_u32 s4, s92, 0x2000
	s_addc_u32 s5, s93, 0
	s_mov_b32 m0, s15
	v_lshl_add_u64 v[244:245], s[4:5], 0, v[184:185]
	ds_read_b128 v[162:165], v230 offset:32768
	ds_read_b128 v[166:169], v230 offset:33792
	ds_read_b128 v[192:195], v230 offset:34816
	ds_read_b128 v[196:199], v230 offset:35840
	ds_read_b128 v[200:203], v230 offset:36864
	ds_read_b128 v[204:207], v230 offset:37888
	ds_read_b128 v[232:235], v230 offset:38912
	ds_read_b128 v[236:239], v230 offset:39936
	global_load_lds_dwordx4 v[244:245], off
	v_lshl_add_u64 v[244:245], s[4:5], 0, v[182:183]
	s_mov_b32 m0, s17
	s_nop 0
	global_load_lds_dwordx4 v[244:245], off
	s_waitcnt vmcnt(8)
	s_waitcnt lgkmcnt(0)
	s_barrier
	s_setprio 1
	v_mfma_f32_16x16x32_bf16 v[130:133], v[74:77], v[162:165], v[130:133]
	v_mfma_f32_16x16x32_bf16 v[118:121], v[82:85], v[162:165], v[118:121]
	v_mfma_f32_16x16x32_bf16 v[110:113], v[74:77], v[192:195], v[110:113]
	v_mfma_f32_16x16x32_bf16 v[102:105], v[82:85], v[192:195], v[102:105]
	v_mfma_f32_16x16x32_bf16 v[94:97], v[74:77], v[200:203], v[94:97]
	v_mfma_f32_16x16x32_bf16 v[86:89], v[82:85], v[200:203], v[86:89]
	v_mfma_f32_16x16x32_bf16 v[70:73], v[74:77], v[232:235], v[70:73]
	v_mfma_f32_16x16x32_bf16 v[54:57], v[82:85], v[232:235], v[54:57]
	v_mfma_f32_16x16x32_bf16 v[130:133], v[78:81], v[166:169], v[130:133]
	v_mfma_f32_16x16x32_bf16 v[118:121], v[90:93], v[166:169], v[118:121]
	v_mfma_f32_16x16x32_bf16 v[110:113], v[78:81], v[196:199], v[110:113]
	v_mfma_f32_16x16x32_bf16 v[102:105], v[90:93], v[196:199], v[102:105]
	v_mfma_f32_16x16x32_bf16 v[94:97], v[78:81], v[204:207], v[94:97]
	v_mfma_f32_16x16x32_bf16 v[86:89], v[90:93], v[204:207], v[86:89]
	v_mfma_f32_16x16x32_bf16 v[70:73], v[78:81], v[236:239], v[70:73]
	v_mfma_f32_16x16x32_bf16 v[54:57], v[90:93], v[236:239], v[54:57]
	v_mfma_f32_16x16x32_bf16 v[150:153], v[122:125], v[162:165], v[150:153]
	v_mfma_f32_16x16x32_bf16 v[146:149], v[154:157], v[162:165], v[146:149]
	v_mfma_f32_16x16x32_bf16 v[142:145], v[122:125], v[192:195], v[142:145]
	v_mfma_f32_16x16x32_bf16 v[138:141], v[154:157], v[192:195], v[138:141]
	v_mfma_f32_16x16x32_bf16 v[126:129], v[122:125], v[200:203], v[126:129]
	v_mfma_f32_16x16x32_bf16 v[114:117], v[154:157], v[200:203], v[114:117]
	v_mfma_f32_16x16x32_bf16 v[106:109], v[122:125], v[232:235], v[106:109]
	v_mfma_f32_16x16x32_bf16 v[98:101], v[154:157], v[232:235], v[98:101]
	v_mfma_f32_16x16x32_bf16 v[150:153], v[134:137], v[166:169], v[150:153]
	v_mfma_f32_16x16x32_bf16 v[146:149], v[158:161], v[166:169], v[146:149]
	v_mfma_f32_16x16x32_bf16 v[142:145], v[134:137], v[196:199], v[142:145]
	v_mfma_f32_16x16x32_bf16 v[138:141], v[158:161], v[196:199], v[138:141]
	v_mfma_f32_16x16x32_bf16 v[126:129], v[134:137], v[204:207], v[126:129]
	v_mfma_f32_16x16x32_bf16 v[114:117], v[158:161], v[204:207], v[114:117]
	v_mfma_f32_16x16x32_bf16 v[106:109], v[134:137], v[236:239], v[106:109]
	v_mfma_f32_16x16x32_bf16 v[98:101], v[158:161], v[236:239], v[98:101]
	s_setprio 0
	s_barrier
; #define PG8_STAGE(bufoff, gbase, voff) do { _Pragma("unroll") for (int _i = 0; _i < 2; ++_i) \
;         __builtin_amdgcn_global_load_lds((const unsigned*)((const char*)(gbase) + (voff)[_i]), (LAS unsigned*)(lds + (bufoff) + ldsw + _i * 8192), 16, 0, 0); } while (0)
; #define PG8_LDA(dst, b, h) do { _Pragma("unroll") for (int m = 0; m < 4; ++m) _Pragma("unroll") for (int k = 0; k < 2; ++k) dst[m][k] = *(const LAS bf16x8*)(lds + PG8_SA(b, h) + aoff + m * 2048 + k * 1024); } while (0)
; #define PG8_MMA(ai, bj, At, Bt) do { __builtin_amdgcn_s_setprio(1); _Pragma("unroll") for (int m = 0; m < 4; ++m) _Pragma("unroll") for (int n = 0; n < 2; ++n) _Pragma("unroll") for (int k = 0; k < 2; ++k) \
;         acc[ai][bj][m][n] = __builtin_amdgcn_mfma_f32_16x16x32_bf16(Bt[n][k], At[m][k], acc[ai][bj][m][n], 0, 0, 0); __builtin_amdgcn_s_setprio(0); } while (0)
; #define PG8_WAIT_V(n) asm volatile("s_waitcnt vmcnt(" #n ")" ::: "memory")
; #define PG8_WAIT_L(n) asm volatile("s_waitcnt lgkmcnt(" #n ")" ::: "memory")
; #define PG8_BAR __builtin_amdgcn_s_barrier()
; #define PG8_SCHED __builtin_amdgcn_sched_barrier(0)
; template <bool ALIGN_EPI, class Epi, class Sched>
; DEV void gemm_phase(LAS unsigned char* lds, const Gemm g, const Sched& S, const Epi& E) {
;     ...
;             PG8_LDA(At, 1, 1); PG8_STAGE(PG8_SB(1, 0), b3, voffB); PG8_STAGE(PG8_SB(1, 1), b3 + hstep, voffB); PG8_STAGE(PG8_SA(1, 0), a3, voffA);
;             PG8_WAIT_V(8); PG8_WAIT_L(0); PG8_BAR; PG8_MMA(1, 0, At, B0); PG8_MMA(1, 1, At, B1); PG8_BAR; PG8_SCHED;
;         }
;         if (ALIGN_EPI) { if (wr == 0) PG8_BAR; }
	s_add_i32 s4, s24, s8
	v_lshl_add_u64 v[208:209], v[208:209], 0, s[30:31]
	s_mov_b32 m0, s4
	ds_read_b128 v[162:165], v230 offset:49152
	ds_read_b128 v[166:169], v230 offset:50176
	ds_read_b128 v[192:195], v230 offset:51200
	ds_read_b128 v[196:199], v230 offset:52224
	ds_read_b128 v[200:203], v230 offset:53248
	ds_read_b128 v[204:207], v230 offset:54272
	ds_read_b128 v[232:235], v230 offset:55296
	ds_read_b128 v[236:239], v230 offset:56320
	global_load_lds_dwordx4 v[208:209], off
	s_add_i32 m0, s4, 0x2000
	s_add_u32 s4, s90, 0x40080
	v_lshl_add_u64 v[208:209], v[214:215], 0, s[30:31]
	s_addc_u32 s5, s91, 0
	s_add_i32 s24, s25, s8
	global_load_lds_dwordx4 v[208:209], off
	v_lshl_add_u64 v[208:209], s[4:5], 0, v[0:1]
	s_mov_b32 m0, s24
	s_nop 0
	global_load_lds_dwordx4 v[208:209], off
	v_lshl_add_u64 v[208:209], s[4:5], 0, v[180:181]
	s_add_i32 m0, s24, 0x2000
	s_nop 0
	global_load_lds_dwordx4 v[208:209], off
	v_lshl_add_u64 v[208:209], v[240:241], 0, s[30:31]
	s_mov_b32 m0, s94
	s_nop 0
	global_load_lds_dwordx4 v[208:209], off
	v_lshl_add_u64 v[208:209], v[242:243], 0, s[30:31]
	s_mov_b32 m0, s95
	s_nop 0
	global_load_lds_dwordx4 v[208:209], off
	s_waitcnt vmcnt(8)
	s_waitcnt lgkmcnt(0)
	s_barrier
	s_setprio 1
	v_mfma_f32_16x16x32_bf16 v[46:49], v[74:77], v[162:165], v[46:49]
	v_mfma_f32_16x16x32_bf16 v[38:41], v[82:85], v[162:165], v[38:41]
	v_mfma_f32_16x16x32_bf16 v[30:33], v[74:77], v[192:195], v[30:33]
	v_mfma_f32_16x16x32_bf16 v[14:17], v[82:85], v[192:195], v[14:17]
	v_mfma_f32_16x16x32_bf16 v[26:29], v[74:77], v[200:203], v[26:29]
	v_mfma_f32_16x16x32_bf16 v[10:13], v[82:85], v[200:203], v[10:13]
	v_mfma_f32_16x16x32_bf16 v[22:25], v[74:77], v[232:235], v[22:25]
	v_mfma_f32_16x16x32_bf16 v[6:9], v[82:85], v[232:235], v[6:9]
	v_mfma_f32_16x16x32_bf16 v[46:49], v[78:81], v[166:169], v[46:49]
	v_mfma_f32_16x16x32_bf16 v[38:41], v[90:93], v[166:169], v[38:41]
	v_mfma_f32_16x16x32_bf16 v[30:33], v[78:81], v[196:199], v[30:33]
	v_mfma_f32_16x16x32_bf16 v[14:17], v[90:93], v[196:199], v[14:17]
	v_mfma_f32_16x16x32_bf16 v[26:29], v[78:81], v[204:207], v[26:29]
	v_mfma_f32_16x16x32_bf16 v[10:13], v[90:93], v[204:207], v[10:13]
	v_mfma_f32_16x16x32_bf16 v[22:25], v[78:81], v[236:239], v[22:25]
	v_mfma_f32_16x16x32_bf16 v[6:9], v[90:93], v[236:239], v[6:9]
	v_mfma_f32_16x16x32_bf16 v[62:65], v[122:125], v[162:165], v[62:65]
	v_mfma_f32_16x16x32_bf16 v[90:93], v[134:137], v[166:169], v[62:65]
	v_mfma_f32_16x16x32_bf16 v[62:65], v[154:157], v[162:165], v[66:69]
	v_mfma_f32_16x16x32_bf16 v[58:61], v[122:125], v[192:195], v[58:61]
	v_mfma_f32_16x16x32_bf16 v[50:53], v[154:157], v[192:195], v[50:53]
	v_mfma_f32_16x16x32_bf16 v[42:45], v[122:125], v[200:203], v[42:45]
	v_mfma_f32_16x16x32_bf16 v[34:37], v[154:157], v[200:203], v[34:37]
	v_mfma_f32_16x16x32_bf16 v[18:21], v[122:125], v[232:235], v[18:21]
	v_mfma_f32_16x16x32_bf16 v[2:5], v[154:157], v[232:235], v[2:5]
	v_mfma_f32_16x16x32_bf16 v[74:77], v[158:161], v[166:169], v[62:65]
	v_mfma_f32_16x16x32_bf16 v[58:61], v[134:137], v[196:199], v[58:61]
	v_mfma_f32_16x16x32_bf16 v[50:53], v[158:161], v[196:199], v[50:53]
	v_mfma_f32_16x16x32_bf16 v[42:45], v[134:137], v[204:207], v[42:45]
	v_mfma_f32_16x16x32_bf16 v[34:37], v[158:161], v[204:207], v[34:37]
	v_mfma_f32_16x16x32_bf16 v[18:21], v[134:137], v[236:239], v[18:21]
	v_mfma_f32_16x16x32_bf16 v[2:5], v[158:161], v[236:239], v[2:5]
	s_setprio 0
	s_barrier
	s_add_i32 s49, s49, 2
	s_add_u32 s21, s21, 0x100
	s_addc_u32 s48, s48, 0
	s_cmp_gt_u32 s49, 13
	s_mov_b64 s[4:5], s[6:7]
	s_cbranch_scc0 .LBB0_28
	s_and_b64 vcc, exec, s[52:53]
	s_cbranch_vccz .LBB0_31
	s_barrier

; #define PG8_STAGE(bufoff, gbase, voff) do { _Pragma("unroll") for (int _i = 0; _i < 2; ++_i) \
;         __builtin_amdgcn_global_load_lds((const unsigned*)((const char*)(gbase) + (voff)[_i]), (LAS unsigned*)(lds + (bufoff) + ldsw + _i * 8192), 16, 0, 0); } while (0)
; #define PG8_LDA(dst, b, h) do { _Pragma("unroll") for (int m = 0; m < 4; ++m) _Pragma("unroll") for (int k = 0; k < 2; ++k) dst[m][k] = *(const LAS bf16x8*)(lds + PG8_SA(b, h) + aoff + m * 2048 + k * 1024); } while (0)
; #define PG8_LDB(dst, b, h) do { _Pragma("unroll") for (int n = 0; n < 2; ++n) _Pragma("unroll") for (int k = 0; k < 2; ++k) dst[n][k] = *(const LAS bf16x8*)(lds + PG8_SB(b, h) + boff + n * 2048 + k * 1024); } while (0)
; #define PG8_MMA(ai, bj, At, Bt) do { __builtin_amdgcn_s_setprio(1); _Pragma("unroll") for (int m = 0; m < 4; ++m) _Pragma("unroll") for (int n = 0; n < 2; ++n) _Pragma("unroll") for (int k = 0; k < 2; ++k) \
;         acc[ai][bj][m][n] = __builtin_amdgcn_mfma_f32_16x16x32_bf16(Bt[n][k], At[m][k], acc[ai][bj][m][n], 0, 0, 0); __builtin_amdgcn_s_setprio(0); } while (0)
; #define PG8_WAIT_V(n) asm volatile("s_waitcnt vmcnt(" #n ")" ::: "memory")
; #define PG8_WAIT_L(n) asm volatile("s_waitcnt lgkmcnt(" #n ")" ::: "memory")
; #define PG8_BAR __builtin_amdgcn_s_barrier()
; #define PG8_SCHED __builtin_amdgcn_sched_barrier(0)
; template <bool ALIGN_EPI, class Epi, class Sched>
; DEV void gemm_phase(LAS unsigned char* lds, const Gemm g, const Sched& S, const Epi& E) {
;     ...
;         for (int t = 0; t < nt; t += 2) {
;             const bool last = (t == nt - 2);
;             const char* a1 = cA + (size_t)(t + 1) * kstep;
;             const char* a2 = last ? nA : cA + (size_t)(t + 2) * kstep; const char* b2 = last ? nB : cB + (size_t)(t + 2) * kstep;
;             const char* a3 = a2 + kstep; const char* b3 = b2 + kstep;
;             PG8_LDB(B0, 0, 0); PG8_LDB(B1, 0, 1); PG8_SCHED; PG8_LDA(At, 0, 0); PG8_STAGE(PG8_SA(1, 1), a1 + hstepA, voffA);
;             PG8_WAIT_V(8); PG8_WAIT_L(0); PG8_BAR; PG8_MMA(0, 0, At, B0); PG8_MMA(0, 1, At, B1); PG8_BAR; PG8_SCHED;
;             PG8_LDA(At, 0, 1); PG8_STAGE(PG8_SB(0, 0), b2, voffB); PG8_STAGE(PG8_SB(0, 1), b2 + hstep, voffB); PG8_STAGE(PG8_SA(0, 0), a2, voffA);
;             PG8_WAIT_V(8); PG8_WAIT_L(0); PG8_BAR; PG8_MMA(1, 0, At, B0); PG8_MMA(1, 1, At, B1); PG8_BAR; PG8_SCHED;
.LBB0_69:
	s_add_u32 s6, s4, 0xfffc0080
	s_addc_u32 s7, s5, -1
	s_add_i32 s86, 0, 0x10000
	s_cmp_eq_u32 s85, 12
	s_cselect_b32 s79, s51, s7
	s_cselect_b32 s78, s81, s6
	s_cselect_b32 s7, s49, s84
	s_cselect_b32 s6, s82, s83
	s_add_i32 s88, 0, 0x14000
	v_add_u32_e32 v142, s86, v186
	v_add_u32_e32 v168, s88, v186
	ds_read_b128 v[130:133], v142
	ds_read_b128 v[134:137], v142 offset:1024
	ds_read_b128 v[138:141], v142 offset:2048
	ds_read_b128 v[142:145], v142 offset:3072
	ds_read_b128 v[146:149], v168
	ds_read_b128 v[150:153], v168 offset:1024
	ds_read_b128 v[164:167], v168 offset:2048
	ds_read_b128 v[180:183], v168 offset:3072
	v_lshl_add_u64 v[168:169], s[4:5], 0, v[160:161]
	s_add_i32 m0, s12, 0xc000
	ds_read_b128 v[190:193], v188
	ds_read_b128 v[194:197], v188 offset:1024
	ds_read_b128 v[198:201], v188 offset:2048
	ds_read_b128 v[202:205], v188 offset:3072
	ds_read_b128 v[206:209], v188 offset:4096
	ds_read_b128 v[230:233], v188 offset:5120
	ds_read_b128 v[234:237], v188 offset:6144
	ds_read_b128 v[238:241], v188 offset:7168
	global_load_lds_dwordx4 v[168:169], off
	v_lshl_add_u64 v[168:169], s[4:5], 0, v[162:163]
	s_add_i32 m0, s12, 0xe000
	s_nop 0
	global_load_lds_dwordx4 v[168:169], off
	s_waitcnt vmcnt(8)
	s_waitcnt lgkmcnt(0)
	s_barrier
	s_setprio 1
	v_mfma_f32_16x16x32_bf16 v[126:129], v[130:133], v[190:193], v[126:129]
	v_mfma_f32_16x16x32_bf16 v[122:125], v[138:141], v[190:193], v[122:125]
	v_mfma_f32_16x16x32_bf16 v[110:113], v[130:133], v[198:201], v[110:113]
	v_mfma_f32_16x16x32_bf16 v[106:109], v[138:141], v[198:201], v[106:109]
	v_mfma_f32_16x16x32_bf16 v[98:101], v[130:133], v[206:209], v[98:101]
	v_mfma_f32_16x16x32_bf16 v[90:93], v[138:141], v[206:209], v[90:93]
	v_mfma_f32_16x16x32_bf16 v[82:85], v[130:133], v[234:237], v[82:85]
	v_mfma_f32_16x16x32_bf16 v[74:77], v[138:141], v[234:237], v[74:77]
	v_mfma_f32_16x16x32_bf16 v[126:129], v[134:137], v[194:197], v[126:129]
	v_mfma_f32_16x16x32_bf16 v[122:125], v[142:145], v[194:197], v[122:125]
	v_mfma_f32_16x16x32_bf16 v[110:113], v[134:137], v[202:205], v[110:113]
	v_mfma_f32_16x16x32_bf16 v[106:109], v[142:145], v[202:205], v[106:109]
	v_mfma_f32_16x16x32_bf16 v[98:101], v[134:137], v[230:233], v[98:101]
	v_mfma_f32_16x16x32_bf16 v[90:93], v[142:145], v[230:233], v[90:93]
	v_mfma_f32_16x16x32_bf16 v[82:85], v[134:137], v[238:241], v[82:85]
	v_mfma_f32_16x16x32_bf16 v[74:77], v[142:145], v[238:241], v[74:77]
	v_mfma_f32_16x16x32_bf16 v[118:121], v[146:149], v[190:193], v[118:121]
	v_mfma_f32_16x16x32_bf16 v[114:117], v[164:167], v[190:193], v[114:117]
	v_mfma_f32_16x16x32_bf16 v[102:105], v[146:149], v[198:201], v[102:105]
	v_mfma_f32_16x16x32_bf16 v[94:97], v[164:167], v[198:201], v[94:97]
	v_mfma_f32_16x16x32_bf16 v[86:89], v[146:149], v[206:209], v[86:89]
	v_mfma_f32_16x16x32_bf16 v[78:81], v[164:167], v[206:209], v[78:81]
	v_mfma_f32_16x16x32_bf16 v[70:73], v[146:149], v[234:237], v[70:73]
	v_mfma_f32_16x16x32_bf16 v[66:69], v[164:167], v[234:237], v[66:69]
	v_mfma_f32_16x16x32_bf16 v[118:121], v[150:153], v[194:197], v[118:121]
	v_mfma_f32_16x16x32_bf16 v[114:117], v[180:183], v[194:197], v[114:117]
	v_mfma_f32_16x16x32_bf16 v[102:105], v[150:153], v[202:205], v[102:105]
	v_mfma_f32_16x16x32_bf16 v[94:97], v[180:183], v[202:205], v[94:97]
	v_mfma_f32_16x16x32_bf16 v[86:89], v[150:153], v[230:233], v[86:89]
	v_mfma_f32_16x16x32_bf16 v[78:81], v[180:183], v[230:233], v[78:81]
	v_mfma_f32_16x16x32_bf16 v[70:73], v[150:153], v[238:241], v[70:73]
	v_mfma_f32_16x16x32_bf16 v[66:69], v[180:183], v[238:241], v[66:69]
	s_setprio 0
	s_barrier
	s_add_i32 s86, s86, s8
	v_lshl_add_u64 v[168:169], s[6:7], 0, v[0:1]
	s_mov_b32 m0, s86
	ds_read_b128 v[190:193], v188 offset:16384
	ds_read_b128 v[194:197], v188 offset:17408
	ds_read_b128 v[198:201], v188 offset:18432
	ds_read_b128 v[202:205], v188 offset:19456
	ds_read_b128 v[206:209], v188 offset:20480
	ds_read_b128 v[230:233], v188 offset:21504
	ds_read_b128 v[234:237], v188 offset:22528
	ds_read_b128 v[238:241], v188 offset:23552
	global_load_lds_dwordx4 v[168:169], off
	s_add_i32 m0, s86, 0x2000
	s_add_u32 s86, s6, 0x40000
	v_lshl_add_u64 v[184:185], s[6:7], 0, v[154:155]
	s_addc_u32 s87, s7, 0
	s_add_i32 s88, s88, s8
	global_load_lds_dwordx4 v[184:185], off
	v_lshl_add_u64 v[214:215], s[86:87], 0, v[0:1]
	s_mov_b32 m0, s88
	v_lshl_add_u64 v[228:229], s[78:79], 0, v[156:157]
	global_load_lds_dwordx4 v[214:215], off
	v_lshl_add_u64 v[214:215], s[86:87], 0, v[154:155]
	s_add_i32 m0, s88, 0x2000
	s_nop 0
	global_load_lds_dwordx4 v[214:215], off
	v_lshl_add_u64 v[214:215], s[78:79], 0, v[158:159]
	s_mov_b32 m0, s12
	s_nop 0
	global_load_lds_dwordx4 v[214:215], off
	s_mov_b32 m0, s13
	s_nop 0
	global_load_lds_dwordx4 v[228:229], off
	s_waitcnt vmcnt(8)
	s_waitcnt lgkmcnt(0)
	s_barrier
; #define PG8_STAGE(bufoff, gbase, voff) do { _Pragma("unroll") for (int _i = 0; _i < 2; ++_i) \
;         __builtin_amdgcn_global_load_lds((const unsigned*)((const char*)(gbase) + (voff)[_i]), (LAS unsigned*)(lds + (bufoff) + ldsw + _i * 8192), 16, 0, 0); } while (0)
; #define PG8_LDA(dst, b, h) do { _Pragma("unroll") for (int m = 0; m < 4; ++m) _Pragma("unroll") for (int k = 0; k < 2; ++k) dst[m][k] = *(const LAS bf16x8*)(lds + PG8_SA(b, h) + aoff + m * 2048 + k * 1024); } while (0)
; #define PG8_LDB(dst, b, h) do { _Pragma("unroll") for (int n = 0; n < 2; ++n) _Pragma("unroll") for (int k = 0; k < 2; ++k) dst[n][k] = *(const LAS bf16x8*)(lds + PG8_SB(b, h) + boff + n * 2048 + k * 1024); } while (0)
; #define PG8_MMA(ai, bj, At, Bt) do { __builtin_amdgcn_s_setprio(1); _Pragma("unroll") for (int m = 0; m < 4; ++m) _Pragma("unroll") for (int n = 0; n < 2; ++n) _Pragma("unroll") for (int k = 0; k < 2; ++k) \
;         acc[ai][bj][m][n] = __builtin_amdgcn_mfma_f32_16x16x32_bf16(Bt[n][k], At[m][k], acc[ai][bj][m][n], 0, 0, 0); __builtin_amdgcn_s_setprio(0); } while (0)
; #define PG8_WAIT_V(n) asm volatile("s_waitcnt vmcnt(" #n ")" ::: "memory")
; #define PG8_WAIT_L(n) asm volatile("s_waitcnt lgkmcnt(" #n ")" ::: "memory")
; #define PG8_BAR __builtin_amdgcn_s_barrier()
; #define PG8_SCHED __builtin_amdgcn_sched_barrier(0)
; template <bool ALIGN_EPI, class Epi, class Sched>
; DEV void gemm_phase(LAS unsigned char* lds, const Gemm g, const Sched& S, const Epi& E) {
;     ...
;             PG8_WAIT_V(8); PG8_WAIT_L(0); PG8_BAR; PG8_MMA(1, 0, At, B0); PG8_MMA(1, 1, At, B1); PG8_BAR; PG8_SCHED;
;             PG8_LDB(B0, 1, 0); PG8_LDB(B1, 1, 1); PG8_SCHED; PG8_LDA(At, 1, 0); PG8_STAGE(PG8_SA(0, 1), a2 + hstepA, voffA);
;             PG8_WAIT_V(8); PG8_WAIT_L(0); PG8_BAR; PG8_MMA(0, 0, At, B0); PG8_MMA(0, 1, At, B1); PG8_BAR; PG8_SCHED;
	s_setprio 1
	v_mfma_f32_16x16x32_bf16 v[62:65], v[130:133], v[190:193], v[62:65]
	v_mfma_f32_16x16x32_bf16 v[58:61], v[138:141], v[190:193], v[58:61]
	v_mfma_f32_16x16x32_bf16 v[50:53], v[130:133], v[198:201], v[50:53]
	v_mfma_f32_16x16x32_bf16 v[42:45], v[138:141], v[198:201], v[42:45]
	v_mfma_f32_16x16x32_bf16 v[34:37], v[130:133], v[206:209], v[34:37]
	v_mfma_f32_16x16x32_bf16 v[26:29], v[138:141], v[206:209], v[26:29]
	v_mfma_f32_16x16x32_bf16 v[18:21], v[130:133], v[234:237], v[18:21]
	v_mfma_f32_16x16x32_bf16 v[10:13], v[138:141], v[234:237], v[10:13]
	v_mfma_f32_16x16x32_bf16 v[62:65], v[134:137], v[194:197], v[62:65]
	v_mfma_f32_16x16x32_bf16 v[58:61], v[142:145], v[194:197], v[58:61]
	v_mfma_f32_16x16x32_bf16 v[50:53], v[134:137], v[202:205], v[50:53]
	v_mfma_f32_16x16x32_bf16 v[42:45], v[142:145], v[202:205], v[42:45]
	v_mfma_f32_16x16x32_bf16 v[34:37], v[134:137], v[230:233], v[34:37]
	v_mfma_f32_16x16x32_bf16 v[26:29], v[142:145], v[230:233], v[26:29]
	v_mfma_f32_16x16x32_bf16 v[18:21], v[134:137], v[238:241], v[18:21]
	v_mfma_f32_16x16x32_bf16 v[10:13], v[142:145], v[238:241], v[10:13]
	v_mfma_f32_16x16x32_bf16 v[54:57], v[146:149], v[190:193], v[54:57]
	v_mfma_f32_16x16x32_bf16 v[46:49], v[164:167], v[190:193], v[46:49]
	v_mfma_f32_16x16x32_bf16 v[38:41], v[146:149], v[198:201], v[38:41]
	v_mfma_f32_16x16x32_bf16 v[30:33], v[164:167], v[198:201], v[30:33]
	v_mfma_f32_16x16x32_bf16 v[22:25], v[146:149], v[206:209], v[22:25]
	v_mfma_f32_16x16x32_bf16 v[14:17], v[164:167], v[206:209], v[14:17]
	v_mfma_f32_16x16x32_bf16 v[6:9], v[146:149], v[234:237], v[6:9]
	v_mfma_f32_16x16x32_bf16 v[2:5], v[164:167], v[234:237], v[2:5]
	v_mfma_f32_16x16x32_bf16 v[54:57], v[150:153], v[194:197], v[54:57]
	v_mfma_f32_16x16x32_bf16 v[46:49], v[180:183], v[194:197], v[46:49]
	v_mfma_f32_16x16x32_bf16 v[38:41], v[150:153], v[202:205], v[38:41]
	v_mfma_f32_16x16x32_bf16 v[30:33], v[180:183], v[202:205], v[30:33]
	v_mfma_f32_16x16x32_bf16 v[22:25], v[150:153], v[230:233], v[22:25]
	v_mfma_f32_16x16x32_bf16 v[14:17], v[180:183], v[230:233], v[14:17]
	v_mfma_f32_16x16x32_bf16 v[6:9], v[150:153], v[238:241], v[6:9]
	v_mfma_f32_16x16x32_bf16 v[2:5], v[180:183], v[238:241], v[2:5]
	s_setprio 0
	s_barrier
	s_add_i32 s86, 0, 0x18000
	s_add_i32 s87, 0, 0x1c000
	v_add_u32_e32 v142, s86, v186
	v_add_u32_e32 v180, s87, v186
	ds_read_b128 v[130:133], v142
	ds_read_b128 v[134:137], v142 offset:1024
	ds_read_b128 v[138:141], v142 offset:2048
	ds_read_b128 v[142:145], v142 offset:3072
	ds_read_b128 v[146:149], v180
	ds_read_b128 v[150:153], v180 offset:1024
	ds_read_b128 v[164:167], v180 offset:2048
	ds_read_b128 v[180:183], v180 offset:3072
	s_add_u32 s78, s78, 0x40000
	s_addc_u32 s79, s79, 0
	s_mov_b32 m0, s15
	v_lshl_add_u64 v[242:243], s[78:79], 0, v[158:159]
	ds_read_b128 v[190:193], v188 offset:32768
	ds_read_b128 v[194:197], v188 offset:33792
	ds_read_b128 v[198:201], v188 offset:34816
	ds_read_b128 v[202:205], v188 offset:35840
	ds_read_b128 v[206:209], v188 offset:36864
	ds_read_b128 v[230:233], v188 offset:37888
	ds_read_b128 v[234:237], v188 offset:38912
	ds_read_b128 v[238:241], v188 offset:39936
	global_load_lds_dwordx4 v[242:243], off
	v_lshl_add_u64 v[242:243], s[78:79], 0, v[156:157]
	s_mov_b32 m0, s17
	s_nop 0
	global_load_lds_dwordx4 v[242:243], off
	s_waitcnt vmcnt(8)
	s_waitcnt lgkmcnt(0)
	s_barrier
	s_setprio 1
	v_mfma_f32_16x16x32_bf16 v[126:129], v[130:133], v[190:193], v[126:129]
	v_mfma_f32_16x16x32_bf16 v[122:125], v[138:141], v[190:193], v[122:125]
	v_mfma_f32_16x16x32_bf16 v[110:113], v[130:133], v[198:201], v[110:113]
	v_mfma_f32_16x16x32_bf16 v[106:109], v[138:141], v[198:201], v[106:109]
	v_mfma_f32_16x16x32_bf16 v[98:101], v[130:133], v[206:209], v[98:101]
	v_mfma_f32_16x16x32_bf16 v[90:93], v[138:141], v[206:209], v[90:93]
	v_mfma_f32_16x16x32_bf16 v[82:85], v[130:133], v[234:237], v[82:85]
	v_mfma_f32_16x16x32_bf16 v[74:77], v[138:141], v[234:237], v[74:77]
	v_mfma_f32_16x16x32_bf16 v[126:129], v[134:137], v[194:197], v[126:129]
	v_mfma_f32_16x16x32_bf16 v[122:125], v[142:145], v[194:197], v[122:125]
	v_mfma_f32_16x16x32_bf16 v[110:113], v[134:137], v[202:205], v[110:113]
	v_mfma_f32_16x16x32_bf16 v[106:109], v[142:145], v[202:205], v[106:109]
	v_mfma_f32_16x16x32_bf16 v[98:101], v[134:137], v[230:233], v[98:101]
	v_mfma_f32_16x16x32_bf16 v[90:93], v[142:145], v[230:233], v[90:93]
	v_mfma_f32_16x16x32_bf16 v[82:85], v[134:137], v[238:241], v[82:85]
	v_mfma_f32_16x16x32_bf16 v[74:77], v[142:145], v[238:241], v[74:77]
	v_mfma_f32_16x16x32_bf16 v[118:121], v[146:149], v[190:193], v[118:121]
	v_mfma_f32_16x16x32_bf16 v[114:117], v[164:167], v[190:193], v[114:117]
	v_mfma_f32_16x16x32_bf16 v[102:105], v[146:149], v[198:201], v[102:105]
	v_mfma_f32_16x16x32_bf16 v[94:97], v[164:167], v[198:201], v[94:97]
	v_mfma_f32_16x16x32_bf16 v[86:89], v[146:149], v[206:209], v[86:89]
	v_mfma_f32_16x16x32_bf16 v[78:81], v[164:167], v[206:209], v[78:81]
	v_mfma_f32_16x16x32_bf16 v[70:73], v[146:149], v[234:237], v[70:73]
	v_mfma_f32_16x16x32_bf16 v[66:69], v[164:167], v[234:237], v[66:69]
	v_mfma_f32_16x16x32_bf16 v[118:121], v[150:153], v[194:197], v[118:121]
	v_mfma_f32_16x16x32_bf16 v[114:117], v[180:183], v[194:197], v[114:117]
	v_mfma_f32_16x16x32_bf16 v[102:105], v[150:153], v[202:205], v[102:105]
	v_mfma_f32_16x16x32_bf16 v[94:97], v[180:183], v[202:205], v[94:97]
	v_mfma_f32_16x16x32_bf16 v[86:89], v[150:153], v[230:233], v[86:89]
	v_mfma_f32_16x16x32_bf16 v[78:81], v[180:183], v[230:233], v[78:81]
	v_mfma_f32_16x16x32_bf16 v[70:73], v[150:153], v[238:241], v[70:73]
	v_mfma_f32_16x16x32_bf16 v[66:69], v[180:183], v[238:241], v[66:69]
	s_setprio 0
	s_barrier
; #define PG8_STAGE(bufoff, gbase, voff) do { _Pragma("unroll") for (int _i = 0; _i < 2; ++_i) \
;         __builtin_amdgcn_global_load_lds((const unsigned*)((const char*)(gbase) + (voff)[_i]), (LAS unsigned*)(lds + (bufoff) + ldsw + _i * 8192), 16, 0, 0); } while (0)
; #define PG8_LDA(dst, b, h) do { _Pragma("unroll") for (int m = 0; m < 4; ++m) _Pragma("unroll") for (int k = 0; k < 2; ++k) dst[m][k] = *(const LAS bf16x8*)(lds + PG8_SA(b, h) + aoff + m * 2048 + k * 1024); } while (0)
; #define PG8_LDB(dst, b, h) do { _Pragma("unroll") for (int n = 0; n < 2; ++n) _Pragma("unroll") for (int k = 0; k < 2; ++k) dst[n][k] = *(const LAS bf16x8*)(lds + PG8_SB(b, h) + boff + n * 2048 + k * 1024); } while (0)
; #define PG8_WAIT_V(n) asm volatile("s_waitcnt vmcnt(" #n ")" ::: "memory")
; #define PG8_WAIT_L(n) asm volatile("s_waitcnt lgkmcnt(" #n ")" ::: "memory")
; template <bool ALIGN_EPI, class Epi, class Sched>
; DEV void gemm_phase(LAS unsigned char* lds, const Gemm g, const Sched& S, const Epi& E) {
;     ...
;         for (int t = 0; t < nt; t += 2) {
;             const bool last = (t == nt - 2);
;             const char* a1 = cA + (size_t)(t + 1) * kstep;
;             const char* a2 = last ? nA : cA + (size_t)(t + 2) * kstep; const char* b2 = last ? nB : cB + (size_t)(t + 2) * kstep;
;             const char* a3 = a2 + kstep; const char* b3 = b2 + kstep;
;             PG8_LDB(B0, 0, 0); PG8_LDB(B1, 0, 1); PG8_SCHED; PG8_LDA(At, 0, 0); PG8_STAGE(PG8_SA(1, 1), a1 + hstepA, voffA);
;             PG8_WAIT_V(8); PG8_WAIT_L(0); PG8_BAR; PG8_MMA(0, 0, At, B0); PG8_MMA(0, 1, At, B1); PG8_BAR; PG8_SCHED;
;             PG8_LDA(At, 0, 1); PG8_STAGE(PG8_SB(0, 0), b2, voffB); PG8_STAGE(PG8_SB(0, 1), b2 + hstep, voffB); PG8_STAGE(PG8_SA(0, 0), a2, voffA);
;             PG8_WAIT_V(8); PG8_WAIT_L(0); PG8_BAR; PG8_MMA(1, 0, At, B0); PG8_MMA(1, 1, At, B1); PG8_BAR; PG8_SCHED;
;             PG8_LDB(B0, 1, 0); PG8_LDB(B1, 1, 1); PG8_SCHED; PG8_LDA(At, 1, 0); PG8_STAGE(PG8_SA(0, 1), a2 + hstepA, voffA);
;             PG8_WAIT_V(8); PG8_WAIT_L(0); PG8_BAR; PG8_MMA(0, 0, At, B0); PG8_MMA(0, 1, At, B1); PG8_BAR; PG8_SCHED;
;             PG8_LDA(At, 1, 1); PG8_STAGE(PG8_SB(1, 0), b3, voffB); PG8_STAGE(PG8_SB(1, 1), b3 + hstep, voffB); PG8_STAGE(PG8_SA(1, 0), a3, voffA);
;             PG8_WAIT_V(8); PG8_WAIT_L(0); PG8_BAR; PG8_MMA(1, 0, At, B0); PG8_MMA(1, 1, At, B1); PG8_BAR; PG8_SCHED;
	s_add_i32 s78, s86, s8
	v_lshl_add_u64 v[168:169], v[168:169], 0, s[30:31]
	s_mov_b32 m0, s78
	ds_read_b128 v[190:193], v188 offset:49152
	ds_read_b128 v[194:197], v188 offset:50176
	ds_read_b128 v[198:201], v188 offset:51200
	ds_read_b128 v[202:205], v188 offset:52224
	ds_read_b128 v[206:209], v188 offset:53248
	ds_read_b128 v[230:233], v188 offset:54272
	ds_read_b128 v[234:237], v188 offset:55296
	ds_read_b128 v[238:241], v188 offset:56320
	global_load_lds_dwordx4 v[168:169], off
	s_add_i32 m0, s78, 0x2000
	s_add_u32 s6, s6, 0x40080
	v_lshl_add_u64 v[168:169], v[184:185], 0, s[30:31]
	s_addc_u32 s7, s7, 0
	s_add_i32 s78, s87, s8
	global_load_lds_dwordx4 v[168:169], off
	v_lshl_add_u64 v[168:169], s[6:7], 0, v[0:1]
	s_mov_b32 m0, s78
	s_nop 0
	global_load_lds_dwordx4 v[168:169], off
	v_lshl_add_u64 v[168:169], s[6:7], 0, v[154:155]
	s_add_i32 m0, s78, 0x2000
	s_nop 0
	global_load_lds_dwordx4 v[168:169], off
	v_lshl_add_u64 v[168:169], v[214:215], 0, s[30:31]
	s_mov_b32 m0, s20
	s_nop 0
	global_load_lds_dwordx4 v[168:169], off
	v_lshl_add_u64 v[168:169], v[228:229], 0, s[30:31]
	s_mov_b32 m0, s21
	s_nop 0
	global_load_lds_dwordx4 v[168:169], off
	s_waitcnt vmcnt(8)
	s_waitcnt lgkmcnt(0)
	s_barrier
	s_setprio 1
	v_mfma_f32_16x16x32_bf16 v[62:65], v[130:133], v[190:193], v[62:65]
	v_mfma_f32_16x16x32_bf16 v[58:61], v[138:141], v[190:193], v[58:61]
	v_mfma_f32_16x16x32_bf16 v[50:53], v[130:133], v[198:201], v[50:53]
	v_mfma_f32_16x16x32_bf16 v[42:45], v[138:141], v[198:201], v[42:45]
	v_mfma_f32_16x16x32_bf16 v[34:37], v[130:133], v[206:209], v[34:37]
	v_mfma_f32_16x16x32_bf16 v[26:29], v[138:141], v[206:209], v[26:29]
	v_mfma_f32_16x16x32_bf16 v[18:21], v[130:133], v[234:237], v[18:21]
	v_mfma_f32_16x16x32_bf16 v[10:13], v[138:141], v[234:237], v[10:13]
	v_mfma_f32_16x16x32_bf16 v[62:65], v[134:137], v[194:197], v[62:65]
	v_mfma_f32_16x16x32_bf16 v[58:61], v[142:145], v[194:197], v[58:61]
	v_mfma_f32_16x16x32_bf16 v[50:53], v[134:137], v[202:205], v[50:53]
	v_mfma_f32_16x16x32_bf16 v[42:45], v[142:145], v[202:205], v[42:45]
	v_mfma_f32_16x16x32_bf16 v[34:37], v[134:137], v[230:233], v[34:37]
	v_mfma_f32_16x16x32_bf16 v[26:29], v[142:145], v[230:233], v[26:29]
	v_mfma_f32_16x16x32_bf16 v[18:21], v[134:137], v[238:241], v[18:21]
	v_mfma_f32_16x16x32_bf16 v[10:13], v[142:145], v[238:241], v[10:13]
	v_mfma_f32_16x16x32_bf16 v[54:57], v[146:149], v[190:193], v[54:57]
	v_mfma_f32_16x16x32_bf16 v[46:49], v[164:167], v[190:193], v[46:49]
	v_mfma_f32_16x16x32_bf16 v[38:41], v[146:149], v[198:201], v[38:41]
	v_mfma_f32_16x16x32_bf16 v[30:33], v[164:167], v[198:201], v[30:33]
	v_mfma_f32_16x16x32_bf16 v[22:25], v[146:149], v[206:209], v[22:25]
	v_mfma_f32_16x16x32_bf16 v[14:17], v[164:167], v[206:209], v[14:17]
	v_mfma_f32_16x16x32_bf16 v[6:9], v[146:149], v[234:237], v[6:9]
	v_mfma_f32_16x16x32_bf16 v[2:5], v[164:167], v[234:237], v[2:5]
	v_mfma_f32_16x16x32_bf16 v[54:57], v[150:153], v[194:197], v[54:57]
	v_mfma_f32_16x16x32_bf16 v[46:49], v[180:183], v[194:197], v[46:49]
	v_mfma_f32_16x16x32_bf16 v[38:41], v[150:153], v[202:205], v[38:41]
	v_mfma_f32_16x16x32_bf16 v[30:33], v[180:183], v[202:205], v[30:33]
	v_mfma_f32_16x16x32_bf16 v[22:25], v[150:153], v[230:233], v[22:25]
	v_mfma_f32_16x16x32_bf16 v[14:17], v[180:183], v[230:233], v[14:17]
	v_mfma_f32_16x16x32_bf16 v[6:9], v[150:153], v[238:241], v[6:9]
	v_mfma_f32_16x16x32_bf16 v[2:5], v[180:183], v[238:241], v[2:5]
	s_setprio 0
	s_barrier
	s_add_i32 s85, s85, 2
	s_add_u32 s4, s4, 0x100
	s_addc_u32 s5, s5, 0
	s_add_u32 s83, s83, 0x100
	s_addc_u32 s84, s84, 0
	s_cmp_gt_u32 s85, 13
	s_cbranch_scc0 .LBB0_69
	s_and_b64 vcc, exec, s[44:45]
	s_cbranch_vccz .LBB0_72
	s_barrier

; #define PG8_STAGE(bufoff, gbase, voff) do { _Pragma("unroll") for (int _i = 0; _i < 2; ++_i) \
;         __builtin_amdgcn_global_load_lds((const unsigned*)((const char*)(gbase) + (voff)[_i]), (LAS unsigned*)(lds + (bufoff) + ldsw + _i * 8192), 16, 0, 0); } while (0)
; #define PG8_LDA(dst, b, h) do { _Pragma("unroll") for (int m = 0; m < 4; ++m) _Pragma("unroll") for (int k = 0; k < 2; ++k) dst[m][k] = *(const LAS bf16x8*)(lds + PG8_SA(b, h) + aoff + m * 2048 + k * 1024); } while (0)
; #define PG8_LDB(dst, b, h) do { _Pragma("unroll") for (int n = 0; n < 2; ++n) _Pragma("unroll") for (int k = 0; k < 2; ++k) dst[n][k] = *(const LAS bf16x8*)(lds + PG8_SB(b, h) + boff + n * 2048 + k * 1024); } while (0)
; #define PG8_MMA(ai, bj, At, Bt) do { __builtin_amdgcn_s_setprio(1); _Pragma("unroll") for (int m = 0; m < 4; ++m) _Pragma("unroll") for (int n = 0; n < 2; ++n) _Pragma("unroll") for (int k = 0; k < 2; ++k) \
;         acc[ai][bj][m][n] = __builtin_amdgcn_mfma_f32_16x16x32_bf16(Bt[n][k], At[m][k], acc[ai][bj][m][n], 0, 0, 0); __builtin_amdgcn_s_setprio(0); } while (0)
; #define PG8_WAIT_V(n) asm volatile("s_waitcnt vmcnt(" #n ")" ::: "memory")
; #define PG8_BAR __builtin_amdgcn_s_barrier()
; template <bool ALIGN_EPI, class Epi, class Sched>
; DEV void gemm_phase(LAS unsigned char* lds, const Gemm g, const Sched& S, const Epi& E) {
;     ...
;         const char* nA = has_next ? (const char*)g.A + (size_t)nxt.pm * tstep : cA; const char* nB = has_next ? (const char*)g.Bt + (size_t)nxt.pn * tstep : cB;
;         for (int t = 0; t < nt; t += 2) {
;             const bool last = (t == nt - 2);
;             const char* a1 = cA + (size_t)(t + 1) * kstep;
;             const char* a2 = last ? nA : cA + (size_t)(t + 2) * kstep; const char* b2 = last ? nB : cB + (size_t)(t + 2) * kstep;
;             const char* a3 = a2 + kstep; const char* b3 = b2 + kstep;
;             PG8_LDB(B0, 0, 0); PG8_LDB(B1, 0, 1); PG8_SCHED; PG8_LDA(At, 0, 0); PG8_STAGE(PG8_SA(1, 1), a1 + hstepA, voffA);
;             PG8_WAIT_V(8); PG8_WAIT_L(0); PG8_BAR; PG8_MMA(0, 0, At, B0); PG8_MMA(0, 1, At, B1); PG8_BAR; PG8_SCHED;
;             PG8_LDA(At, 0, 1); PG8_STAGE(PG8_SB(0, 0), b2, voffB); PG8_STAGE(PG8_SB(0, 1), b2 + hstep, voffB); PG8_STAGE(PG8_SA(0, 0), a2, voffA);
;             PG8_WAIT_V(8); PG8_WAIT_L(0); PG8_BAR; PG8_MMA(1, 0, At, B0); PG8_MMA(1, 1, At, B1); PG8_BAR; PG8_SCHED;
.LBB0_91:
	s_add_u32 s6, s4, 0xfffc0080
	s_addc_u32 s7, s5, -1
	s_add_i32 s85, 0, 0x10000
	s_cmp_eq_u32 s84, 12
	s_cselect_b32 s43, s51, s7
	s_cselect_b32 s42, s80, s6
	v_add_u32_e32 v0, s85, v198
	s_cselect_b32 s7, s53, s83
	s_cselect_b32 s6, s81, s82
	s_add_i32 s88, 0, 0x14000
	ds_read_b128 v[132:135], v0
	ds_read_b128 v[136:139], v0 offset:1024
	ds_read_b128 v[140:143], v0 offset:2048
	ds_read_b128 v[144:147], v0 offset:3072
	v_add_u32_e32 v0, s88, v198
	ds_read_b128 v[148:151], v0
	s_waitcnt lgkmcnt(0)
	ds_read_b128 v[152:155], v0 offset:1024
	ds_read_b128 v[156:159], v0 offset:2048
	ds_read_b128 v[160:163], v0 offset:3072
	v_lshl_add_u64 v[2:3], s[4:5], 0, v[186:187]
	s_add_i32 m0, s12, 0xc000
	ds_read_b128 v[164:167], v200
	ds_read_b128 v[190:193], v200 offset:1024
	ds_read_b128 v[194:197], v200 offset:2048
	ds_read_b128 v[202:205], v200 offset:3072
	ds_read_b128 v[206:209], v200 offset:4096
	ds_read_b128 v[230:233], v200 offset:5120
	ds_read_b128 v[234:237], v200 offset:6144
	ds_read_b128 v[238:241], v200 offset:7168
	global_load_lds_dwordx4 v[2:3], off
	v_lshl_add_u64 v[2:3], s[4:5], 0, v[188:189]
	s_add_i32 m0, s12, 0xe000
	s_nop 0
	global_load_lds_dwordx4 v[2:3], off
	s_waitcnt vmcnt(8)
	s_waitcnt lgkmcnt(0)
	s_barrier
	s_setprio 1
	v_mfma_f32_16x16x32_bf16 v[128:131], v[132:135], v[164:167], v[128:131]
	v_mfma_f32_16x16x32_bf16 v[124:127], v[140:143], v[164:167], v[124:127]
	v_mfma_f32_16x16x32_bf16 v[120:123], v[132:135], v[194:197], v[120:123]
	v_mfma_f32_16x16x32_bf16 v[116:119], v[140:143], v[194:197], v[116:119]
	v_mfma_f32_16x16x32_bf16 v[112:115], v[132:135], v[206:209], v[112:115]
	v_mfma_f32_16x16x32_bf16 v[108:111], v[140:143], v[206:209], v[108:111]
	v_mfma_f32_16x16x32_bf16 v[104:107], v[132:135], v[234:237], v[104:107]
	v_mfma_f32_16x16x32_bf16 v[100:103], v[140:143], v[234:237], v[100:103]
	v_mfma_f32_16x16x32_bf16 v[128:131], v[136:139], v[190:193], v[128:131]
	v_mfma_f32_16x16x32_bf16 v[124:127], v[144:147], v[190:193], v[124:127]
	v_mfma_f32_16x16x32_bf16 v[120:123], v[136:139], v[202:205], v[120:123]
	v_mfma_f32_16x16x32_bf16 v[116:119], v[144:147], v[202:205], v[116:119]
	v_mfma_f32_16x16x32_bf16 v[112:115], v[136:139], v[230:233], v[112:115]
	v_mfma_f32_16x16x32_bf16 v[108:111], v[144:147], v[230:233], v[108:111]
	v_mfma_f32_16x16x32_bf16 v[104:107], v[136:139], v[238:241], v[104:107]
	v_mfma_f32_16x16x32_bf16 v[100:103], v[144:147], v[238:241], v[100:103]
	v_mfma_f32_16x16x32_bf16 v[96:99], v[148:151], v[164:167], v[96:99]
	v_mfma_f32_16x16x32_bf16 v[92:95], v[156:159], v[164:167], v[92:95]
	v_mfma_f32_16x16x32_bf16 v[88:91], v[148:151], v[194:197], v[88:91]
	v_mfma_f32_16x16x32_bf16 v[84:87], v[156:159], v[194:197], v[84:87]
	v_mfma_f32_16x16x32_bf16 v[80:83], v[148:151], v[206:209], v[80:83]
	v_mfma_f32_16x16x32_bf16 v[76:79], v[156:159], v[206:209], v[76:79]
	v_mfma_f32_16x16x32_bf16 v[72:75], v[148:151], v[234:237], v[72:75]
	v_mfma_f32_16x16x32_bf16 v[68:71], v[156:159], v[234:237], v[68:71]
	v_mfma_f32_16x16x32_bf16 v[96:99], v[152:155], v[190:193], v[96:99]
	v_mfma_f32_16x16x32_bf16 v[92:95], v[160:163], v[190:193], v[92:95]
	v_mfma_f32_16x16x32_bf16 v[88:91], v[152:155], v[202:205], v[88:91]
	v_mfma_f32_16x16x32_bf16 v[84:87], v[160:163], v[202:205], v[84:87]
	v_mfma_f32_16x16x32_bf16 v[80:83], v[152:155], v[230:233], v[80:83]
	v_mfma_f32_16x16x32_bf16 v[76:79], v[160:163], v[230:233], v[76:79]
	v_mfma_f32_16x16x32_bf16 v[72:75], v[152:155], v[238:241], v[72:75]
	v_mfma_f32_16x16x32_bf16 v[68:71], v[160:163], v[238:241], v[68:71]
	s_setprio 0
	s_barrier
	s_add_i32 s85, s85, s8
	v_lshl_add_u64 v[214:215], s[6:7], 0, v[182:183]
	s_mov_b32 m0, s85
	ds_read_b128 v[164:167], v200 offset:16384
	ds_read_b128 v[190:193], v200 offset:17408
	ds_read_b128 v[194:197], v200 offset:18432
	ds_read_b128 v[202:205], v200 offset:19456
	ds_read_b128 v[206:209], v200 offset:20480
	ds_read_b128 v[230:233], v200 offset:21504
	ds_read_b128 v[234:237], v200 offset:22528
	ds_read_b128 v[238:241], v200 offset:23552
	global_load_lds_dwordx4 v[214:215], off
	s_add_i32 m0, s85, 0x2000
	s_add_u32 s86, s6, 0x40000
	v_lshl_add_u64 v[228:229], s[6:7], 0, v[168:169]
	s_addc_u32 s87, s7, 0
	s_add_i32 s85, s88, s8
	global_load_lds_dwordx4 v[228:229], off
	v_lshl_add_u64 v[2:3], s[86:87], 0, v[182:183]
	s_mov_b32 m0, s85
	v_lshl_add_u64 v[242:243], s[42:43], 0, v[184:185]
	global_load_lds_dwordx4 v[2:3], off
	v_lshl_add_u64 v[2:3], s[86:87], 0, v[168:169]
	s_add_i32 m0, s85, 0x2000
	v_lshl_add_u64 v[244:245], s[42:43], 0, v[180:181]
	global_load_lds_dwordx4 v[2:3], off
	s_mov_b32 m0, s12
	s_nop 0
	global_load_lds_dwordx4 v[242:243], off
	s_mov_b32 m0, s13
	s_nop 0
	global_load_lds_dwordx4 v[244:245], off
	s_waitcnt vmcnt(8)
	s_waitcnt lgkmcnt(0)
	s_barrier
; #define PG8_STAGE(bufoff, gbase, voff) do { _Pragma("unroll") for (int _i = 0; _i < 2; ++_i) \
;         __builtin_amdgcn_global_load_lds((const unsigned*)((const char*)(gbase) + (voff)[_i]), (LAS unsigned*)(lds + (bufoff) + ldsw + _i * 8192), 16, 0, 0); } while (0)
; #define PG8_LDA(dst, b, h) do { _Pragma("unroll") for (int m = 0; m < 4; ++m) _Pragma("unroll") for (int k = 0; k < 2; ++k) dst[m][k] = *(const LAS bf16x8*)(lds + PG8_SA(b, h) + aoff + m * 2048 + k * 1024); } while (0)
; #define PG8_LDB(dst, b, h) do { _Pragma("unroll") for (int n = 0; n < 2; ++n) _Pragma("unroll") for (int k = 0; k < 2; ++k) dst[n][k] = *(const LAS bf16x8*)(lds + PG8_SB(b, h) + boff + n * 2048 + k * 1024); } while (0)
; #define PG8_MMA(ai, bj, At, Bt) do { __builtin_amdgcn_s_setprio(1); _Pragma("unroll") for (int m = 0; m < 4; ++m) _Pragma("unroll") for (int n = 0; n < 2; ++n) _Pragma("unroll") for (int k = 0; k < 2; ++k) \
;         acc[ai][bj][m][n] = __builtin_amdgcn_mfma_f32_16x16x32_bf16(Bt[n][k], At[m][k], acc[ai][bj][m][n], 0, 0, 0); __builtin_amdgcn_s_setprio(0); } while (0)
; #define PG8_WAIT_V(n) asm volatile("s_waitcnt vmcnt(" #n ")" ::: "memory")
; #define PG8_WAIT_L(n) asm volatile("s_waitcnt lgkmcnt(" #n ")" ::: "memory")
; #define PG8_BAR __builtin_amdgcn_s_barrier()
; #define PG8_SCHED __builtin_amdgcn_sched_barrier(0)
; template <bool ALIGN_EPI, class Epi, class Sched>
; DEV void gemm_phase(LAS unsigned char* lds, const Gemm g, const Sched& S, const Epi& E) {
;     ...
;             PG8_WAIT_V(8); PG8_WAIT_L(0); PG8_BAR; PG8_MMA(1, 0, At, B0); PG8_MMA(1, 1, At, B1); PG8_BAR; PG8_SCHED;
;             PG8_LDB(B0, 1, 0); PG8_LDB(B1, 1, 1); PG8_SCHED; PG8_LDA(At, 1, 0); PG8_STAGE(PG8_SA(0, 1), a2 + hstepA, voffA);
;             PG8_WAIT_V(8); PG8_WAIT_L(0); PG8_BAR; PG8_MMA(0, 0, At, B0); PG8_MMA(0, 1, At, B1); PG8_BAR; PG8_SCHED;
	s_setprio 1
	v_mfma_f32_16x16x32_bf16 v[64:67], v[132:135], v[164:167], v[64:67]
	v_mfma_f32_16x16x32_bf16 v[60:63], v[140:143], v[164:167], v[60:63]
	v_mfma_f32_16x16x32_bf16 v[56:59], v[132:135], v[194:197], v[56:59]
	v_mfma_f32_16x16x32_bf16 v[52:55], v[140:143], v[194:197], v[52:55]
	v_mfma_f32_16x16x32_bf16 v[48:51], v[132:135], v[206:209], v[48:51]
	v_mfma_f32_16x16x32_bf16 v[44:47], v[140:143], v[206:209], v[44:47]
	v_mfma_f32_16x16x32_bf16 v[40:43], v[132:135], v[234:237], v[40:43]
	v_mfma_f32_16x16x32_bf16 v[36:39], v[140:143], v[234:237], v[36:39]
	v_mfma_f32_16x16x32_bf16 v[64:67], v[136:139], v[190:193], v[64:67]
	v_mfma_f32_16x16x32_bf16 v[60:63], v[144:147], v[190:193], v[60:63]
	v_mfma_f32_16x16x32_bf16 v[56:59], v[136:139], v[202:205], v[56:59]
	v_mfma_f32_16x16x32_bf16 v[52:55], v[144:147], v[202:205], v[52:55]
	v_mfma_f32_16x16x32_bf16 v[48:51], v[136:139], v[230:233], v[48:51]
	v_mfma_f32_16x16x32_bf16 v[44:47], v[144:147], v[230:233], v[44:47]
	v_mfma_f32_16x16x32_bf16 v[40:43], v[136:139], v[238:241], v[40:43]
	v_mfma_f32_16x16x32_bf16 v[36:39], v[144:147], v[238:241], v[36:39]
	v_mfma_f32_16x16x32_bf16 v[32:35], v[148:151], v[164:167], v[32:35]
	v_mfma_f32_16x16x32_bf16 v[28:31], v[156:159], v[164:167], v[28:31]
	v_mfma_f32_16x16x32_bf16 v[24:27], v[148:151], v[194:197], v[24:27]
	v_mfma_f32_16x16x32_bf16 v[20:23], v[156:159], v[194:197], v[20:23]
	v_mfma_f32_16x16x32_bf16 v[16:19], v[148:151], v[206:209], v[16:19]
	v_mfma_f32_16x16x32_bf16 v[12:15], v[156:159], v[206:209], v[12:15]
	v_mfma_f32_16x16x32_bf16 v[8:11], v[148:151], v[234:237], v[8:11]
	v_mfma_f32_16x16x32_bf16 v[2:5], v[156:159], v[234:237], v[4:7]
	v_mfma_f32_16x16x32_bf16 v[32:35], v[152:155], v[190:193], v[32:35]
	v_mfma_f32_16x16x32_bf16 v[28:31], v[160:163], v[190:193], v[28:31]
	v_mfma_f32_16x16x32_bf16 v[24:27], v[152:155], v[202:205], v[24:27]
	v_mfma_f32_16x16x32_bf16 v[20:23], v[160:163], v[202:205], v[20:23]
	v_mfma_f32_16x16x32_bf16 v[16:19], v[152:155], v[230:233], v[16:19]
	v_mfma_f32_16x16x32_bf16 v[12:15], v[160:163], v[230:233], v[12:15]
	v_mfma_f32_16x16x32_bf16 v[8:11], v[152:155], v[238:241], v[8:11]
	v_mfma_f32_16x16x32_bf16 v[2:5], v[160:163], v[238:241], v[2:5]
	s_setprio 0
	s_barrier
	s_add_i32 s85, 0, 0x18000
	v_add_u32_e32 v0, s85, v198
	s_add_i32 s86, 0, 0x1c000
	ds_read_b128 v[132:135], v0
	ds_read_b128 v[136:139], v0 offset:1024
	ds_read_b128 v[140:143], v0 offset:2048
	ds_read_b128 v[144:147], v0 offset:3072
	v_add_u32_e32 v0, s86, v198
	ds_read_b128 v[148:151], v0
	ds_read_b128 v[152:155], v0 offset:1024
	ds_read_b128 v[156:159], v0 offset:2048
	ds_read_b128 v[160:163], v0 offset:3072
	s_add_u32 s42, s42, 0x40000
	s_addc_u32 s43, s43, 0
	s_mov_b32 m0, s15
	v_lshl_add_u64 v[6:7], s[42:43], 0, v[184:185]
	ds_read_b128 v[164:167], v200 offset:32768
	ds_read_b128 v[190:193], v200 offset:33792
	ds_read_b128 v[194:197], v200 offset:34816
	ds_read_b128 v[202:205], v200 offset:35840
	ds_read_b128 v[206:209], v200 offset:36864
	ds_read_b128 v[230:233], v200 offset:37888
	ds_read_b128 v[234:237], v200 offset:38912
	ds_read_b128 v[238:241], v200 offset:39936
	global_load_lds_dwordx4 v[6:7], off
	v_lshl_add_u64 v[6:7], s[42:43], 0, v[180:181]
	s_mov_b32 m0, s17
	s_nop 0
	global_load_lds_dwordx4 v[6:7], off
	s_waitcnt vmcnt(8)
	s_waitcnt lgkmcnt(0)
	s_barrier
	s_setprio 1
	v_mfma_f32_16x16x32_bf16 v[128:131], v[132:135], v[164:167], v[128:131]
	v_mfma_f32_16x16x32_bf16 v[124:127], v[140:143], v[164:167], v[124:127]
	v_mfma_f32_16x16x32_bf16 v[120:123], v[132:135], v[194:197], v[120:123]
	v_mfma_f32_16x16x32_bf16 v[116:119], v[140:143], v[194:197], v[116:119]
	v_mfma_f32_16x16x32_bf16 v[112:115], v[132:135], v[206:209], v[112:115]
	v_mfma_f32_16x16x32_bf16 v[108:111], v[140:143], v[206:209], v[108:111]
	v_mfma_f32_16x16x32_bf16 v[104:107], v[132:135], v[234:237], v[104:107]
	v_mfma_f32_16x16x32_bf16 v[100:103], v[140:143], v[234:237], v[100:103]
	v_mfma_f32_16x16x32_bf16 v[128:131], v[136:139], v[190:193], v[128:131]
	v_mfma_f32_16x16x32_bf16 v[124:127], v[144:147], v[190:193], v[124:127]
	v_mfma_f32_16x16x32_bf16 v[120:123], v[136:139], v[202:205], v[120:123]
	v_mfma_f32_16x16x32_bf16 v[116:119], v[144:147], v[202:205], v[116:119]
	v_mfma_f32_16x16x32_bf16 v[112:115], v[136:139], v[230:233], v[112:115]
	v_mfma_f32_16x16x32_bf16 v[108:111], v[144:147], v[230:233], v[108:111]
	v_mfma_f32_16x16x32_bf16 v[104:107], v[136:139], v[238:241], v[104:107]
	v_mfma_f32_16x16x32_bf16 v[100:103], v[144:147], v[238:241], v[100:103]
	v_mfma_f32_16x16x32_bf16 v[96:99], v[148:151], v[164:167], v[96:99]
	v_mfma_f32_16x16x32_bf16 v[92:95], v[156:159], v[164:167], v[92:95]
	v_mfma_f32_16x16x32_bf16 v[88:91], v[148:151], v[194:197], v[88:91]
	v_mfma_f32_16x16x32_bf16 v[84:87], v[156:159], v[194:197], v[84:87]
	v_mfma_f32_16x16x32_bf16 v[80:83], v[148:151], v[206:209], v[80:83]
	v_mfma_f32_16x16x32_bf16 v[76:79], v[156:159], v[206:209], v[76:79]
	v_mfma_f32_16x16x32_bf16 v[72:75], v[148:151], v[234:237], v[72:75]
	v_mfma_f32_16x16x32_bf16 v[68:71], v[156:159], v[234:237], v[68:71]
	v_mfma_f32_16x16x32_bf16 v[96:99], v[152:155], v[190:193], v[96:99]
	v_mfma_f32_16x16x32_bf16 v[92:95], v[160:163], v[190:193], v[92:95]
	v_mfma_f32_16x16x32_bf16 v[88:91], v[152:155], v[202:205], v[88:91]
	v_mfma_f32_16x16x32_bf16 v[84:87], v[160:163], v[202:205], v[84:87]
	v_mfma_f32_16x16x32_bf16 v[80:83], v[152:155], v[230:233], v[80:83]
	v_mfma_f32_16x16x32_bf16 v[76:79], v[160:163], v[230:233], v[76:79]
	v_mfma_f32_16x16x32_bf16 v[72:75], v[152:155], v[238:241], v[72:75]
	v_mfma_f32_16x16x32_bf16 v[68:71], v[160:163], v[238:241], v[68:71]
	s_setprio 0
	s_barrier
; #define PG8_STAGE(bufoff, gbase, voff) do { _Pragma("unroll") for (int _i = 0; _i < 2; ++_i) \
;         __builtin_amdgcn_global_load_lds((const unsigned*)((const char*)(gbase) + (voff)[_i]), (LAS unsigned*)(lds + (bufoff) + ldsw + _i * 8192), 16, 0, 0); } while (0)
; #define PG8_LDA(dst, b, h) do { _Pragma("unroll") for (int m = 0; m < 4; ++m) _Pragma("unroll") for (int k = 0; k < 2; ++k) dst[m][k] = *(const LAS bf16x8*)(lds + PG8_SA(b, h) + aoff + m * 2048 + k * 1024); } while (0)
; #define PG8_LDB(dst, b, h) do { _Pragma("unroll") for (int n = 0; n < 2; ++n) _Pragma("unroll") for (int k = 0; k < 2; ++k) dst[n][k] = *(const LAS bf16x8*)(lds + PG8_SB(b, h) + boff + n * 2048 + k * 1024); } while (0)
; #define PG8_WAIT_V(n) asm volatile("s_waitcnt vmcnt(" #n ")" ::: "memory")
; #define PG8_WAIT_L(n) asm volatile("s_waitcnt lgkmcnt(" #n ")" ::: "memory")
; template <bool ALIGN_EPI, class Epi, class Sched>
; DEV void gemm_phase(LAS unsigned char* lds, const Gemm g, const Sched& S, const Epi& E) {
;     ...
;         for (int t = 0; t < nt; t += 2) {
;             const bool last = (t == nt - 2);
;             const char* a1 = cA + (size_t)(t + 1) * kstep;
;             const char* a2 = last ? nA : cA + (size_t)(t + 2) * kstep; const char* b2 = last ? nB : cB + (size_t)(t + 2) * kstep;
;             const char* a3 = a2 + kstep; const char* b3 = b2 + kstep;
;             PG8_LDB(B0, 0, 0); PG8_LDB(B1, 0, 1); PG8_SCHED; PG8_LDA(At, 0, 0); PG8_STAGE(PG8_SA(1, 1), a1 + hstepA, voffA);
;             PG8_WAIT_V(8); PG8_WAIT_L(0); PG8_BAR; PG8_MMA(0, 0, At, B0); PG8_MMA(0, 1, At, B1); PG8_BAR; PG8_SCHED;
;             PG8_LDA(At, 0, 1); PG8_STAGE(PG8_SB(0, 0), b2, voffB); PG8_STAGE(PG8_SB(0, 1), b2 + hstep, voffB); PG8_STAGE(PG8_SA(0, 0), a2, voffA);
;             PG8_WAIT_V(8); PG8_WAIT_L(0); PG8_BAR; PG8_MMA(1, 0, At, B0); PG8_MMA(1, 1, At, B1); PG8_BAR; PG8_SCHED;
;             PG8_LDB(B0, 1, 0); PG8_LDB(B1, 1, 1); PG8_SCHED; PG8_LDA(At, 1, 0); PG8_STAGE(PG8_SA(0, 1), a2 + hstepA, voffA);
;             PG8_WAIT_V(8); PG8_WAIT_L(0); PG8_BAR; PG8_MMA(0, 0, At, B0); PG8_MMA(0, 1, At, B1); PG8_BAR; PG8_SCHED;
;             PG8_LDA(At, 1, 1); PG8_STAGE(PG8_SB(1, 0), b3, voffB); PG8_STAGE(PG8_SB(1, 1), b3 + hstep, voffB); PG8_STAGE(PG8_SA(1, 0), a3, voffA);
;             PG8_WAIT_V(8); PG8_WAIT_L(0); PG8_BAR; PG8_MMA(1, 0, At, B0); PG8_MMA(1, 1, At, B1); PG8_BAR; PG8_SCHED;
	s_add_i32 s42, s85, s8
	v_lshl_add_u64 v[6:7], v[214:215], 0, s[30:31]
	s_mov_b32 m0, s42
	ds_read_b128 v[164:167], v200 offset:49152
	ds_read_b128 v[190:193], v200 offset:50176
	ds_read_b128 v[194:197], v200 offset:51200
	ds_read_b128 v[202:205], v200 offset:52224
	ds_read_b128 v[206:209], v200 offset:53248
	ds_read_b128 v[230:233], v200 offset:54272
	ds_read_b128 v[234:237], v200 offset:55296
	ds_read_b128 v[238:241], v200 offset:56320
	global_load_lds_dwordx4 v[6:7], off
	s_add_i32 m0, s42, 0x2000
	s_add_u32 s6, s6, 0x40080
	v_lshl_add_u64 v[6:7], v[228:229], 0, s[30:31]
	s_addc_u32 s7, s7, 0
	s_add_i32 s42, s86, s8
	global_load_lds_dwordx4 v[6:7], off
	v_lshl_add_u64 v[6:7], s[6:7], 0, v[182:183]
	s_mov_b32 m0, s42
	s_nop 0
	global_load_lds_dwordx4 v[6:7], off
	v_lshl_add_u64 v[6:7], s[6:7], 0, v[168:169]
	s_add_i32 m0, s42, 0x2000
	s_nop 0
	global_load_lds_dwordx4 v[6:7], off
	v_lshl_add_u64 v[6:7], v[242:243], 0, s[30:31]
	s_mov_b32 m0, s20
	s_nop 0
	global_load_lds_dwordx4 v[6:7], off
	v_lshl_add_u64 v[6:7], v[244:245], 0, s[30:31]
	s_mov_b32 m0, s21
	s_nop 0
	global_load_lds_dwordx4 v[6:7], off
	s_waitcnt vmcnt(8)
	s_waitcnt lgkmcnt(0)
	s_barrier
	s_setprio 1
	v_mfma_f32_16x16x32_bf16 v[64:67], v[132:135], v[164:167], v[64:67]
	v_mfma_f32_16x16x32_bf16 v[60:63], v[140:143], v[164:167], v[60:63]
	v_mfma_f32_16x16x32_bf16 v[56:59], v[132:135], v[194:197], v[56:59]
	v_mfma_f32_16x16x32_bf16 v[52:55], v[140:143], v[194:197], v[52:55]
	v_mfma_f32_16x16x32_bf16 v[48:51], v[132:135], v[206:209], v[48:51]
	v_mfma_f32_16x16x32_bf16 v[44:47], v[140:143], v[206:209], v[44:47]
	v_mfma_f32_16x16x32_bf16 v[40:43], v[132:135], v[234:237], v[40:43]
	v_mfma_f32_16x16x32_bf16 v[36:39], v[140:143], v[234:237], v[36:39]
	v_mfma_f32_16x16x32_bf16 v[64:67], v[136:139], v[190:193], v[64:67]
	v_mfma_f32_16x16x32_bf16 v[60:63], v[144:147], v[190:193], v[60:63]
	v_mfma_f32_16x16x32_bf16 v[56:59], v[136:139], v[202:205], v[56:59]
	v_mfma_f32_16x16x32_bf16 v[52:55], v[144:147], v[202:205], v[52:55]
	v_mfma_f32_16x16x32_bf16 v[48:51], v[136:139], v[230:233], v[48:51]
	v_mfma_f32_16x16x32_bf16 v[44:47], v[144:147], v[230:233], v[44:47]
	v_mfma_f32_16x16x32_bf16 v[40:43], v[136:139], v[238:241], v[40:43]
	v_mfma_f32_16x16x32_bf16 v[36:39], v[144:147], v[238:241], v[36:39]
	v_mfma_f32_16x16x32_bf16 v[32:35], v[148:151], v[164:167], v[32:35]
	v_mfma_f32_16x16x32_bf16 v[28:31], v[156:159], v[164:167], v[28:31]
	v_mfma_f32_16x16x32_bf16 v[24:27], v[148:151], v[194:197], v[24:27]
	v_mfma_f32_16x16x32_bf16 v[20:23], v[156:159], v[194:197], v[20:23]
	v_mfma_f32_16x16x32_bf16 v[16:19], v[148:151], v[206:209], v[16:19]
	v_mfma_f32_16x16x32_bf16 v[12:15], v[156:159], v[206:209], v[12:15]
	v_mfma_f32_16x16x32_bf16 v[6:9], v[148:151], v[234:237], v[8:11]
	v_mfma_f32_16x16x32_bf16 v[2:5], v[156:159], v[234:237], v[2:5]
	v_mfma_f32_16x16x32_bf16 v[32:35], v[152:155], v[190:193], v[32:35]
	v_mfma_f32_16x16x32_bf16 v[28:31], v[160:163], v[190:193], v[28:31]
	v_mfma_f32_16x16x32_bf16 v[24:27], v[152:155], v[202:205], v[24:27]
	v_mfma_f32_16x16x32_bf16 v[20:23], v[160:163], v[202:205], v[20:23]
	v_mfma_f32_16x16x32_bf16 v[16:19], v[152:155], v[230:233], v[16:19]
	v_mfma_f32_16x16x32_bf16 v[12:15], v[160:163], v[230:233], v[12:15]
	v_mfma_f32_16x16x32_bf16 v[8:11], v[152:155], v[238:241], v[6:9]
	v_mfma_f32_16x16x32_bf16 v[4:7], v[160:163], v[238:241], v[2:5]
	s_setprio 0
	s_barrier
	s_add_i32 s84, s84, 2
	s_add_u32 s4, s4, 0x100
	s_addc_u32 s5, s5, 0
	s_add_u32 s82, s82, 0x100
	s_addc_u32 s83, s83, 0
	s_cmp_gt_u32 s84, 13
	s_cbranch_scc0 .LBB0_91
	s_and_b64 vcc, exec, s[48:49]
	s_cbranch_vccz .LBB0_94
	s_barrier

; #define PG8_STAGE(bufoff, gbase, voff) do { _Pragma("unroll") for (int _i = 0; _i < 2; ++_i) \
;         __builtin_amdgcn_global_load_lds((const unsigned*)((const char*)(gbase) + (voff)[_i]), (LAS unsigned*)(lds + (bufoff) + ldsw + _i * 8192), 16, 0, 0); } while (0)
; #define PG8_LDA(dst, b, h) do { _Pragma("unroll") for (int m = 0; m < 4; ++m) _Pragma("unroll") for (int k = 0; k < 2; ++k) dst[m][k] = *(const LAS bf16x8*)(lds + PG8_SA(b, h) + aoff + m * 2048 + k * 1024); } while (0)
; #define PG8_LDB(dst, b, h) do { _Pragma("unroll") for (int n = 0; n < 2; ++n) _Pragma("unroll") for (int k = 0; k < 2; ++k) dst[n][k] = *(const LAS bf16x8*)(lds + PG8_SB(b, h) + boff + n * 2048 + k * 1024); } while (0)
; #define PG8_MMA(ai, bj, At, Bt) do { __builtin_amdgcn_s_setprio(1); _Pragma("unroll") for (int m = 0; m < 4; ++m) _Pragma("unroll") for (int n = 0; n < 2; ++n) _Pragma("unroll") for (int k = 0; k < 2; ++k) \
;         acc[ai][bj][m][n] = __builtin_amdgcn_mfma_f32_16x16x32_bf16(Bt[n][k], At[m][k], acc[ai][bj][m][n], 0, 0, 0); __builtin_amdgcn_s_setprio(0); } while (0)
; #define PG8_WAIT_V(n) asm volatile("s_waitcnt vmcnt(" #n ")" ::: "memory")
; #define PG8_WAIT_L(n) asm volatile("s_waitcnt lgkmcnt(" #n ")" ::: "memory")
; #define PG8_BAR __builtin_amdgcn_s_barrier()
; #define PG8_SCHED __builtin_amdgcn_sched_barrier(0)
; template <bool ALIGN_EPI, class Epi, class Sched>
; DEV void gemm_phase(LAS unsigned char* lds, const Gemm g, const Sched& S, const Epi& E) {
;     ...
;             const bool last = (t == nt - 2);
;             const char* a1 = cA + (size_t)(t + 1) * kstep;
;             const char* a2 = last ? nA : cA + (size_t)(t + 2) * kstep; const char* b2 = last ? nB : cB + (size_t)(t + 2) * kstep;
;             const char* a3 = a2 + kstep; const char* b3 = b2 + kstep;
;             PG8_LDB(B0, 0, 0); PG8_LDB(B1, 0, 1); PG8_SCHED; PG8_LDA(At, 0, 0); PG8_STAGE(PG8_SA(1, 1), a1 + hstepA, voffA);
;             PG8_WAIT_V(8); PG8_WAIT_L(0); PG8_BAR; PG8_MMA(0, 0, At, B0); PG8_MMA(0, 1, At, B1); PG8_BAR; PG8_SCHED;
;             PG8_LDA(At, 0, 1); PG8_STAGE(PG8_SB(0, 0), b2, voffB); PG8_STAGE(PG8_SB(0, 1), b2 + hstep, voffB); PG8_STAGE(PG8_SA(0, 0), a2, voffA);
;             PG8_WAIT_V(8); PG8_WAIT_L(0); PG8_BAR; PG8_MMA(1, 0, At, B0); PG8_MMA(1, 1, At, B1); PG8_BAR; PG8_SCHED;
.LBB0_315:
	s_add_u32 s6, s4, 0x100
	s_addc_u32 s7, s5, 0
	s_add_i32 s93, 0, 0x10000
	s_cmp_eq_u32 s87, 12
	s_cselect_b32 s95, s17, s7
	s_cselect_b32 s94, s36, s6
	v_add_u32_e32 v0, s93, v171
	s_cselect_b32 s47, s41, s85
	s_cselect_b32 s46, s64, s70
	s_add_i32 vcc_lo, 0, 0x14000
	ds_read_b128 v[130:133], v0
	ds_read_b128 v[134:137], v0 offset:1024
	ds_read_b128 v[138:141], v0 offset:2048
	ds_read_b128 v[142:145], v0 offset:3072
	v_add_u32_e32 v0, vcc_lo, v171
	ds_read_b128 v[146:149], v0
	ds_read_b128 v[150:153], v0 offset:1024
	ds_read_b128 v[154:157], v0 offset:2048
	ds_read_b128 v[158:161], v0 offset:3072
	v_lshl_add_u64 v[246:247], s[4:5], 0, v[190:191]
	s_add_i32 m0, s13, 0xc000
	ds_read_b128 v[162:165], v203
	ds_read_b128 v[166:169], v203 offset:1024
	ds_read_b128 v[194:197], v203 offset:2048
	ds_read_b128 v[206:209], v203 offset:3072
	ds_read_b128 v[230:233], v203 offset:4096
	ds_read_b128 v[234:237], v203 offset:5120
	ds_read_b128 v[238:241], v203 offset:6144
	ds_read_b128 v[242:245], v203 offset:7168
	global_load_lds_dwordx4 v[246:247], off
	v_lshl_add_u64 v[246:247], s[4:5], 0, v[192:193]
	s_add_i32 m0, s13, 0xe000
	s_nop 0
	global_load_lds_dwordx4 v[246:247], off
	s_waitcnt vmcnt(8)
	s_waitcnt lgkmcnt(0)
	s_barrier
	s_setprio 1
	v_mfma_f32_16x16x32_bf16 v[126:129], v[130:133], v[162:165], v[126:129]
	v_mfma_f32_16x16x32_bf16 v[122:125], v[138:141], v[162:165], v[122:125]
	v_mfma_f32_16x16x32_bf16 v[110:113], v[130:133], v[194:197], v[110:113]
	v_mfma_f32_16x16x32_bf16 v[106:109], v[138:141], v[194:197], v[106:109]
	v_mfma_f32_16x16x32_bf16 v[94:97], v[130:133], v[230:233], v[94:97]
	v_mfma_f32_16x16x32_bf16 v[90:93], v[138:141], v[230:233], v[90:93]
	v_mfma_f32_16x16x32_bf16 v[78:81], v[130:133], v[238:241], v[78:81]
	v_mfma_f32_16x16x32_bf16 v[74:77], v[138:141], v[238:241], v[74:77]
	v_mfma_f32_16x16x32_bf16 v[126:129], v[134:137], v[166:169], v[126:129]
	v_mfma_f32_16x16x32_bf16 v[122:125], v[142:145], v[166:169], v[122:125]
	v_mfma_f32_16x16x32_bf16 v[110:113], v[134:137], v[206:209], v[110:113]
	v_mfma_f32_16x16x32_bf16 v[106:109], v[142:145], v[206:209], v[106:109]
	v_mfma_f32_16x16x32_bf16 v[94:97], v[134:137], v[234:237], v[94:97]
	v_mfma_f32_16x16x32_bf16 v[90:93], v[142:145], v[234:237], v[90:93]
	v_mfma_f32_16x16x32_bf16 v[78:81], v[134:137], v[242:245], v[78:81]
	v_mfma_f32_16x16x32_bf16 v[74:77], v[142:145], v[242:245], v[74:77]
	v_mfma_f32_16x16x32_bf16 v[118:121], v[146:149], v[162:165], v[118:121]
	v_mfma_f32_16x16x32_bf16 v[114:117], v[154:157], v[162:165], v[114:117]
	v_mfma_f32_16x16x32_bf16 v[102:105], v[146:149], v[194:197], v[102:105]
	v_mfma_f32_16x16x32_bf16 v[98:101], v[154:157], v[194:197], v[98:101]
	v_mfma_f32_16x16x32_bf16 v[86:89], v[146:149], v[230:233], v[86:89]
	v_mfma_f32_16x16x32_bf16 v[82:85], v[154:157], v[230:233], v[82:85]
	v_mfma_f32_16x16x32_bf16 v[70:73], v[146:149], v[238:241], v[70:73]
	v_mfma_f32_16x16x32_bf16 v[66:69], v[154:157], v[238:241], v[66:69]
	v_mfma_f32_16x16x32_bf16 v[118:121], v[150:153], v[166:169], v[118:121]
	v_mfma_f32_16x16x32_bf16 v[114:117], v[158:161], v[166:169], v[114:117]
	v_mfma_f32_16x16x32_bf16 v[102:105], v[150:153], v[206:209], v[102:105]
	v_mfma_f32_16x16x32_bf16 v[98:101], v[158:161], v[206:209], v[98:101]
	v_mfma_f32_16x16x32_bf16 v[86:89], v[150:153], v[234:237], v[86:89]
	v_mfma_f32_16x16x32_bf16 v[82:85], v[158:161], v[234:237], v[82:85]
	v_mfma_f32_16x16x32_bf16 v[70:73], v[150:153], v[242:245], v[70:73]
	v_mfma_f32_16x16x32_bf16 v[66:69], v[158:161], v[242:245], v[66:69]
	s_setprio 0
	s_barrier
	s_add_i32 s4, s93, s12
	v_lshl_add_u64 v[246:247], s[46:47], 0, v[184:185]
	s_mov_b32 m0, s4
	ds_read_b128 v[162:165], v203 offset:16384
	ds_read_b128 v[166:169], v203 offset:17408
	ds_read_b128 v[194:197], v203 offset:18432
	ds_read_b128 v[206:209], v203 offset:19456
	ds_read_b128 v[230:233], v203 offset:20480
	ds_read_b128 v[234:237], v203 offset:21504
	ds_read_b128 v[238:241], v203 offset:22528
	ds_read_b128 v[242:245], v203 offset:23552
	global_load_lds_dwordx4 v[246:247], off
	s_add_i32 m0, s4, 0x2000
	s_add_u32 s4, s46, 0x40000
	v_lshl_add_u64 v[248:249], s[46:47], 0, v[180:181]
	s_addc_u32 s5, s47, 0
	s_add_i32 s93, vcc_lo, s12
	global_load_lds_dwordx4 v[248:249], off
	v_lshl_add_u64 v[250:251], s[4:5], 0, v[184:185]
	s_mov_b32 m0, s93
	v_lshl_add_u64 v[228:229], s[94:95], 0, v[182:183]
	global_load_lds_dwordx4 v[250:251], off
	v_lshl_add_u64 v[250:251], s[4:5], 0, v[180:181]
	s_add_i32 m0, s93, 0x2000
	s_nop 0
	global_load_lds_dwordx4 v[250:251], off
	v_lshl_add_u64 v[250:251], s[94:95], 0, v[186:187]
	s_mov_b32 m0, s13
	s_nop 0
	global_load_lds_dwordx4 v[250:251], off
	s_mov_b32 m0, s15
	s_nop 0
	global_load_lds_dwordx4 v[228:229], off
	s_waitcnt vmcnt(8)
	s_waitcnt lgkmcnt(0)
	s_barrier
; #define PG8_STAGE(bufoff, gbase, voff) do { _Pragma("unroll") for (int _i = 0; _i < 2; ++_i) \
;         __builtin_amdgcn_global_load_lds((const unsigned*)((const char*)(gbase) + (voff)[_i]), (LAS unsigned*)(lds + (bufoff) + ldsw + _i * 8192), 16, 0, 0); } while (0)
; #define PG8_LDA(dst, b, h) do { _Pragma("unroll") for (int m = 0; m < 4; ++m) _Pragma("unroll") for (int k = 0; k < 2; ++k) dst[m][k] = *(const LAS bf16x8*)(lds + PG8_SA(b, h) + aoff + m * 2048 + k * 1024); } while (0)
; #define PG8_LDB(dst, b, h) do { _Pragma("unroll") for (int n = 0; n < 2; ++n) _Pragma("unroll") for (int k = 0; k < 2; ++k) dst[n][k] = *(const LAS bf16x8*)(lds + PG8_SB(b, h) + boff + n * 2048 + k * 1024); } while (0)
; #define PG8_MMA(ai, bj, At, Bt) do { __builtin_amdgcn_s_setprio(1); _Pragma("unroll") for (int m = 0; m < 4; ++m) _Pragma("unroll") for (int n = 0; n < 2; ++n) _Pragma("unroll") for (int k = 0; k < 2; ++k) \
;         acc[ai][bj][m][n] = __builtin_amdgcn_mfma_f32_16x16x32_bf16(Bt[n][k], At[m][k], acc[ai][bj][m][n], 0, 0, 0); __builtin_amdgcn_s_setprio(0); } while (0)
; #define PG8_WAIT_V(n) asm volatile("s_waitcnt vmcnt(" #n ")" ::: "memory")
; #define PG8_WAIT_L(n) asm volatile("s_waitcnt lgkmcnt(" #n ")" ::: "memory")
; #define PG8_BAR __builtin_amdgcn_s_barrier()
; #define PG8_SCHED __builtin_amdgcn_sched_barrier(0)
; template <bool ALIGN_EPI, class Epi, class Sched>
; DEV void gemm_phase(LAS unsigned char* lds, const Gemm g, const Sched& S, const Epi& E) {
;     ...
;             PG8_WAIT_V(8); PG8_WAIT_L(0); PG8_BAR; PG8_MMA(1, 0, At, B0); PG8_MMA(1, 1, At, B1); PG8_BAR; PG8_SCHED;
;             PG8_LDB(B0, 1, 0); PG8_LDB(B1, 1, 1); PG8_SCHED; PG8_LDA(At, 1, 0); PG8_STAGE(PG8_SA(0, 1), a2 + hstepA, voffA);
;             PG8_WAIT_V(8); PG8_WAIT_L(0); PG8_BAR; PG8_MMA(0, 0, At, B0); PG8_MMA(0, 1, At, B1); PG8_BAR; PG8_SCHED;
	s_setprio 1
	v_mfma_f32_16x16x32_bf16 v[62:65], v[130:133], v[162:165], v[62:65]
	v_mfma_f32_16x16x32_bf16 v[58:61], v[138:141], v[162:165], v[58:61]
	v_mfma_f32_16x16x32_bf16 v[46:49], v[130:133], v[194:197], v[46:49]
	v_mfma_f32_16x16x32_bf16 v[42:45], v[138:141], v[194:197], v[42:45]
	v_mfma_f32_16x16x32_bf16 v[30:33], v[130:133], v[230:233], v[30:33]
	v_mfma_f32_16x16x32_bf16 v[26:29], v[138:141], v[230:233], v[26:29]
	v_mfma_f32_16x16x32_bf16 v[14:17], v[130:133], v[238:241], v[14:17]
	v_mfma_f32_16x16x32_bf16 v[10:13], v[138:141], v[238:241], v[10:13]
	v_mfma_f32_16x16x32_bf16 v[62:65], v[134:137], v[166:169], v[62:65]
	v_mfma_f32_16x16x32_bf16 v[58:61], v[142:145], v[166:169], v[58:61]
	v_mfma_f32_16x16x32_bf16 v[46:49], v[134:137], v[206:209], v[46:49]
	v_mfma_f32_16x16x32_bf16 v[42:45], v[142:145], v[206:209], v[42:45]
	v_mfma_f32_16x16x32_bf16 v[30:33], v[134:137], v[234:237], v[30:33]
	v_mfma_f32_16x16x32_bf16 v[26:29], v[142:145], v[234:237], v[26:29]
	v_mfma_f32_16x16x32_bf16 v[14:17], v[134:137], v[242:245], v[14:17]
	v_mfma_f32_16x16x32_bf16 v[10:13], v[142:145], v[242:245], v[10:13]
	v_mfma_f32_16x16x32_bf16 v[54:57], v[146:149], v[162:165], v[54:57]
	v_mfma_f32_16x16x32_bf16 v[50:53], v[154:157], v[162:165], v[50:53]
	v_mfma_f32_16x16x32_bf16 v[38:41], v[146:149], v[194:197], v[38:41]
	v_mfma_f32_16x16x32_bf16 v[34:37], v[154:157], v[194:197], v[34:37]
	v_mfma_f32_16x16x32_bf16 v[22:25], v[146:149], v[230:233], v[22:25]
	v_mfma_f32_16x16x32_bf16 v[18:21], v[154:157], v[230:233], v[18:21]
	v_mfma_f32_16x16x32_bf16 v[6:9], v[146:149], v[238:241], v[6:9]
	v_mfma_f32_16x16x32_bf16 v[2:5], v[154:157], v[238:241], v[2:5]
	v_mfma_f32_16x16x32_bf16 v[54:57], v[150:153], v[166:169], v[54:57]
	v_mfma_f32_16x16x32_bf16 v[50:53], v[158:161], v[166:169], v[50:53]
	v_mfma_f32_16x16x32_bf16 v[38:41], v[150:153], v[206:209], v[38:41]
	v_mfma_f32_16x16x32_bf16 v[34:37], v[158:161], v[206:209], v[34:37]
	v_mfma_f32_16x16x32_bf16 v[22:25], v[150:153], v[234:237], v[22:25]
	v_mfma_f32_16x16x32_bf16 v[18:21], v[158:161], v[234:237], v[18:21]
	v_mfma_f32_16x16x32_bf16 v[6:9], v[150:153], v[242:245], v[6:9]
	v_mfma_f32_16x16x32_bf16 v[2:5], v[158:161], v[242:245], v[2:5]
	s_setprio 0
	s_barrier
	s_add_i32 s93, 0, 0x18000
	v_add_u32_e32 v0, s93, v171
	s_add_i32 vcc_lo, 0, 0x1c000
	ds_read_b128 v[130:133], v0
	ds_read_b128 v[134:137], v0 offset:1024
	ds_read_b128 v[138:141], v0 offset:2048
	ds_read_b128 v[142:145], v0 offset:3072
	v_add_u32_e32 v0, vcc_lo, v171
	ds_read_b128 v[146:149], v0
	ds_read_b128 v[150:153], v0 offset:1024
	ds_read_b128 v[154:157], v0 offset:2048
	ds_read_b128 v[158:161], v0 offset:3072
	s_add_u32 s4, s94, 0x2000
	s_addc_u32 s5, s95, 0
	s_mov_b32 m0, s20
	v_lshl_add_u64 v[214:215], s[4:5], 0, v[186:187]
	ds_read_b128 v[162:165], v203 offset:32768
	ds_read_b128 v[166:169], v203 offset:33792
	ds_read_b128 v[194:197], v203 offset:34816
	ds_read_b128 v[206:209], v203 offset:35840
	ds_read_b128 v[230:233], v203 offset:36864
	ds_read_b128 v[234:237], v203 offset:37888
	ds_read_b128 v[238:241], v203 offset:38912
	ds_read_b128 v[242:245], v203 offset:39936
	global_load_lds_dwordx4 v[214:215], off
	v_lshl_add_u64 v[214:215], s[4:5], 0, v[182:183]
	s_mov_b32 m0, s21
	s_nop 0
	global_load_lds_dwordx4 v[214:215], off
	s_waitcnt vmcnt(8)
	s_waitcnt lgkmcnt(0)
	s_barrier
	s_setprio 1
	v_mfma_f32_16x16x32_bf16 v[126:129], v[130:133], v[162:165], v[126:129]
	v_mfma_f32_16x16x32_bf16 v[122:125], v[138:141], v[162:165], v[122:125]
	v_mfma_f32_16x16x32_bf16 v[110:113], v[130:133], v[194:197], v[110:113]
	v_mfma_f32_16x16x32_bf16 v[106:109], v[138:141], v[194:197], v[106:109]
	v_mfma_f32_16x16x32_bf16 v[94:97], v[130:133], v[230:233], v[94:97]
	v_mfma_f32_16x16x32_bf16 v[90:93], v[138:141], v[230:233], v[90:93]
	v_mfma_f32_16x16x32_bf16 v[78:81], v[130:133], v[238:241], v[78:81]
	v_mfma_f32_16x16x32_bf16 v[74:77], v[138:141], v[238:241], v[74:77]
	v_mfma_f32_16x16x32_bf16 v[126:129], v[134:137], v[166:169], v[126:129]
	v_mfma_f32_16x16x32_bf16 v[122:125], v[142:145], v[166:169], v[122:125]
	v_mfma_f32_16x16x32_bf16 v[110:113], v[134:137], v[206:209], v[110:113]
	v_mfma_f32_16x16x32_bf16 v[106:109], v[142:145], v[206:209], v[106:109]
	v_mfma_f32_16x16x32_bf16 v[94:97], v[134:137], v[234:237], v[94:97]
	v_mfma_f32_16x16x32_bf16 v[90:93], v[142:145], v[234:237], v[90:93]
	v_mfma_f32_16x16x32_bf16 v[78:81], v[134:137], v[242:245], v[78:81]
	v_mfma_f32_16x16x32_bf16 v[74:77], v[142:145], v[242:245], v[74:77]
	v_mfma_f32_16x16x32_bf16 v[118:121], v[146:149], v[162:165], v[118:121]
	v_mfma_f32_16x16x32_bf16 v[114:117], v[154:157], v[162:165], v[114:117]
	v_mfma_f32_16x16x32_bf16 v[102:105], v[146:149], v[194:197], v[102:105]
	v_mfma_f32_16x16x32_bf16 v[98:101], v[154:157], v[194:197], v[98:101]
	v_mfma_f32_16x16x32_bf16 v[86:89], v[146:149], v[230:233], v[86:89]
	v_mfma_f32_16x16x32_bf16 v[82:85], v[154:157], v[230:233], v[82:85]
	v_mfma_f32_16x16x32_bf16 v[70:73], v[146:149], v[238:241], v[70:73]
	v_mfma_f32_16x16x32_bf16 v[66:69], v[154:157], v[238:241], v[66:69]
	v_mfma_f32_16x16x32_bf16 v[118:121], v[150:153], v[166:169], v[118:121]
	v_mfma_f32_16x16x32_bf16 v[114:117], v[158:161], v[166:169], v[114:117]
	v_mfma_f32_16x16x32_bf16 v[102:105], v[150:153], v[206:209], v[102:105]
	v_mfma_f32_16x16x32_bf16 v[98:101], v[158:161], v[206:209], v[98:101]
	v_mfma_f32_16x16x32_bf16 v[86:89], v[150:153], v[234:237], v[86:89]
	v_mfma_f32_16x16x32_bf16 v[82:85], v[158:161], v[234:237], v[82:85]
	v_mfma_f32_16x16x32_bf16 v[70:73], v[150:153], v[242:245], v[70:73]
	v_mfma_f32_16x16x32_bf16 v[66:69], v[158:161], v[242:245], v[66:69]
	s_setprio 0
	s_barrier
; #define PG8_STAGE(bufoff, gbase, voff) do { _Pragma("unroll") for (int _i = 0; _i < 2; ++_i) \
;         __builtin_amdgcn_global_load_lds((const unsigned*)((const char*)(gbase) + (voff)[_i]), (LAS unsigned*)(lds + (bufoff) + ldsw + _i * 8192), 16, 0, 0); } while (0)
; #define PG8_LDA(dst, b, h) do { _Pragma("unroll") for (int m = 0; m < 4; ++m) _Pragma("unroll") for (int k = 0; k < 2; ++k) dst[m][k] = *(const LAS bf16x8*)(lds + PG8_SA(b, h) + aoff + m * 2048 + k * 1024); } while (0)
; #define PG8_LDB(dst, b, h) do { _Pragma("unroll") for (int n = 0; n < 2; ++n) _Pragma("unroll") for (int k = 0; k < 2; ++k) dst[n][k] = *(const LAS bf16x8*)(lds + PG8_SB(b, h) + boff + n * 2048 + k * 1024); } while (0)
; #define PG8_WAIT_V(n) asm volatile("s_waitcnt vmcnt(" #n ")" ::: "memory")
; #define PG8_WAIT_L(n) asm volatile("s_waitcnt lgkmcnt(" #n ")" ::: "memory")
; template <bool ALIGN_EPI, class Epi, class Sched>
; DEV void gemm_phase(LAS unsigned char* lds, const Gemm g, const Sched& S, const Epi& E) {
;     ...
;         for (int t = 0; t < nt; t += 2) {
;             const bool last = (t == nt - 2);
;             const char* a1 = cA + (size_t)(t + 1) * kstep;
;             const char* a2 = last ? nA : cA + (size_t)(t + 2) * kstep; const char* b2 = last ? nB : cB + (size_t)(t + 2) * kstep;
;             const char* a3 = a2 + kstep; const char* b3 = b2 + kstep;
;             PG8_LDB(B0, 0, 0); PG8_LDB(B1, 0, 1); PG8_SCHED; PG8_LDA(At, 0, 0); PG8_STAGE(PG8_SA(1, 1), a1 + hstepA, voffA);
;             PG8_WAIT_V(8); PG8_WAIT_L(0); PG8_BAR; PG8_MMA(0, 0, At, B0); PG8_MMA(0, 1, At, B1); PG8_BAR; PG8_SCHED;
;             PG8_LDA(At, 0, 1); PG8_STAGE(PG8_SB(0, 0), b2, voffB); PG8_STAGE(PG8_SB(0, 1), b2 + hstep, voffB); PG8_STAGE(PG8_SA(0, 0), a2, voffA);
;             PG8_WAIT_V(8); PG8_WAIT_L(0); PG8_BAR; PG8_MMA(1, 0, At, B0); PG8_MMA(1, 1, At, B1); PG8_BAR; PG8_SCHED;
;             PG8_LDB(B0, 1, 0); PG8_LDB(B1, 1, 1); PG8_SCHED; PG8_LDA(At, 1, 0); PG8_STAGE(PG8_SA(0, 1), a2 + hstepA, voffA);
;             PG8_WAIT_V(8); PG8_WAIT_L(0); PG8_BAR; PG8_MMA(0, 0, At, B0); PG8_MMA(0, 1, At, B1); PG8_BAR; PG8_SCHED;
;             PG8_LDA(At, 1, 1); PG8_STAGE(PG8_SB(1, 0), b3, voffB); PG8_STAGE(PG8_SB(1, 1), b3 + hstep, voffB); PG8_STAGE(PG8_SA(1, 0), a3, voffA);
;             PG8_WAIT_V(8); PG8_WAIT_L(0); PG8_BAR; PG8_MMA(1, 0, At, B0); PG8_MMA(1, 1, At, B1); PG8_BAR; PG8_SCHED;
	s_add_i32 s4, s93, s12
	v_lshl_add_u64 v[214:215], v[246:247], 0, s[30:31]
	s_mov_b32 m0, s4
	ds_read_b128 v[162:165], v203 offset:49152
	ds_read_b128 v[166:169], v203 offset:50176
	ds_read_b128 v[194:197], v203 offset:51200
	ds_read_b128 v[206:209], v203 offset:52224
	ds_read_b128 v[230:233], v203 offset:53248
	ds_read_b128 v[234:237], v203 offset:54272
	ds_read_b128 v[238:241], v203 offset:55296
	ds_read_b128 v[242:245], v203 offset:56320
	global_load_lds_dwordx4 v[214:215], off
	s_add_i32 m0, s4, 0x2000
	s_add_u32 s4, s46, 0x40080
	v_lshl_add_u64 v[214:215], v[248:249], 0, s[30:31]
	s_addc_u32 s5, s47, 0
	s_add_i32 s46, vcc_lo, s12
	global_load_lds_dwordx4 v[214:215], off
	v_lshl_add_u64 v[214:215], s[4:5], 0, v[184:185]
	s_mov_b32 m0, s46
	s_nop 0
	global_load_lds_dwordx4 v[214:215], off
	v_lshl_add_u64 v[214:215], s[4:5], 0, v[180:181]
	s_add_i32 m0, s46, 0x2000
	s_nop 0
	global_load_lds_dwordx4 v[214:215], off
	v_lshl_add_u64 v[214:215], v[250:251], 0, s[30:31]
	s_mov_b32 m0, s78
	s_nop 0
	global_load_lds_dwordx4 v[214:215], off
	v_lshl_add_u64 v[214:215], v[228:229], 0, s[30:31]
	s_mov_b32 m0, s79
	s_nop 0
	global_load_lds_dwordx4 v[214:215], off
	s_waitcnt vmcnt(8)
	s_waitcnt lgkmcnt(0)
	s_barrier
	s_setprio 1
	v_mfma_f32_16x16x32_bf16 v[62:65], v[130:133], v[162:165], v[62:65]
	v_mfma_f32_16x16x32_bf16 v[58:61], v[138:141], v[162:165], v[58:61]
	v_mfma_f32_16x16x32_bf16 v[46:49], v[130:133], v[194:197], v[46:49]
	v_mfma_f32_16x16x32_bf16 v[42:45], v[138:141], v[194:197], v[42:45]
	v_mfma_f32_16x16x32_bf16 v[30:33], v[130:133], v[230:233], v[30:33]
	v_mfma_f32_16x16x32_bf16 v[26:29], v[138:141], v[230:233], v[26:29]
	v_mfma_f32_16x16x32_bf16 v[14:17], v[130:133], v[238:241], v[14:17]
	v_mfma_f32_16x16x32_bf16 v[10:13], v[138:141], v[238:241], v[10:13]
	v_mfma_f32_16x16x32_bf16 v[62:65], v[134:137], v[166:169], v[62:65]
	v_mfma_f32_16x16x32_bf16 v[58:61], v[142:145], v[166:169], v[58:61]
	v_mfma_f32_16x16x32_bf16 v[46:49], v[134:137], v[206:209], v[46:49]
	v_mfma_f32_16x16x32_bf16 v[42:45], v[142:145], v[206:209], v[42:45]
	v_mfma_f32_16x16x32_bf16 v[30:33], v[134:137], v[234:237], v[30:33]
	v_mfma_f32_16x16x32_bf16 v[26:29], v[142:145], v[234:237], v[26:29]
	v_mfma_f32_16x16x32_bf16 v[14:17], v[134:137], v[242:245], v[14:17]
	v_mfma_f32_16x16x32_bf16 v[10:13], v[142:145], v[242:245], v[10:13]
	v_mfma_f32_16x16x32_bf16 v[54:57], v[146:149], v[162:165], v[54:57]
	v_mfma_f32_16x16x32_bf16 v[50:53], v[154:157], v[162:165], v[50:53]
	v_mfma_f32_16x16x32_bf16 v[38:41], v[146:149], v[194:197], v[38:41]
	v_mfma_f32_16x16x32_bf16 v[34:37], v[154:157], v[194:197], v[34:37]
	v_mfma_f32_16x16x32_bf16 v[22:25], v[146:149], v[230:233], v[22:25]
	v_mfma_f32_16x16x32_bf16 v[18:21], v[154:157], v[230:233], v[18:21]
	v_mfma_f32_16x16x32_bf16 v[6:9], v[146:149], v[238:241], v[6:9]
	v_mfma_f32_16x16x32_bf16 v[2:5], v[154:157], v[238:241], v[2:5]
	v_mfma_f32_16x16x32_bf16 v[54:57], v[150:153], v[166:169], v[54:57]
	v_mfma_f32_16x16x32_bf16 v[50:53], v[158:161], v[166:169], v[50:53]
	v_mfma_f32_16x16x32_bf16 v[38:41], v[150:153], v[206:209], v[38:41]
	v_mfma_f32_16x16x32_bf16 v[34:37], v[158:161], v[206:209], v[34:37]
	v_mfma_f32_16x16x32_bf16 v[22:25], v[150:153], v[234:237], v[22:25]
	v_mfma_f32_16x16x32_bf16 v[18:21], v[158:161], v[234:237], v[18:21]
	v_mfma_f32_16x16x32_bf16 v[6:9], v[150:153], v[242:245], v[6:9]
	v_mfma_f32_16x16x32_bf16 v[2:5], v[158:161], v[242:245], v[2:5]
	s_setprio 0
	s_barrier
	s_add_i32 s87, s87, 2
	s_add_u32 s70, s70, 0x100
	s_addc_u32 s85, s85, 0
	s_cmp_gt_u32 s87, 13
	s_mov_b64 s[4:5], s[6:7]
	s_cbranch_scc0 .LBB0_315
	s_and_b64 vcc, exec, s[54:55]
	s_cbranch_vccz .LBB0_318
	s_barrier

; #define PG8_STAGE(bufoff, gbase, voff) do { _Pragma("unroll") for (int _i = 0; _i < 2; ++_i) \
;         __builtin_amdgcn_global_load_lds((const unsigned*)((const char*)(gbase) + (voff)[_i]), (LAS unsigned*)(lds + (bufoff) + ldsw + _i * 8192), 16, 0, 0); } while (0)
; #define PG8_LDA(dst, b, h) do { _Pragma("unroll") for (int m = 0; m < 4; ++m) _Pragma("unroll") for (int k = 0; k < 2; ++k) dst[m][k] = *(const LAS bf16x8*)(lds + PG8_SA(b, h) + aoff + m * 2048 + k * 1024); } while (0)
; #define PG8_LDB(dst, b, h) do { _Pragma("unroll") for (int n = 0; n < 2; ++n) _Pragma("unroll") for (int k = 0; k < 2; ++k) dst[n][k] = *(const LAS bf16x8*)(lds + PG8_SB(b, h) + boff + n * 2048 + k * 1024); } while (0)
; #define PG8_MMA(ai, bj, At, Bt) do { __builtin_amdgcn_s_setprio(1); _Pragma("unroll") for (int m = 0; m < 4; ++m) _Pragma("unroll") for (int n = 0; n < 2; ++n) _Pragma("unroll") for (int k = 0; k < 2; ++k) \
;         acc[ai][bj][m][n] = __builtin_amdgcn_mfma_f32_16x16x32_bf16(Bt[n][k], At[m][k], acc[ai][bj][m][n], 0, 0, 0); __builtin_amdgcn_s_setprio(0); } while (0)
; #define PG8_WAIT_V(n) asm volatile("s_waitcnt vmcnt(" #n ")" ::: "memory")
; #define PG8_WAIT_L(n) asm volatile("s_waitcnt lgkmcnt(" #n ")" ::: "memory")
; #define PG8_BAR __builtin_amdgcn_s_barrier()
; #define PG8_SCHED __builtin_amdgcn_sched_barrier(0)
; template <bool ALIGN_EPI, class Epi, class Sched>
; DEV void gemm_phase(LAS unsigned char* lds, const Gemm g, const Sched& S, const Epi& E) {
;     ...
;             const bool last = (t == nt - 2);
;             const char* a1 = cA + (size_t)(t + 1) * kstep;
;             const char* a2 = last ? nA : cA + (size_t)(t + 2) * kstep; const char* b2 = last ? nB : cB + (size_t)(t + 2) * kstep;
;             const char* a3 = a2 + kstep; const char* b3 = b2 + kstep;
;             PG8_LDB(B0, 0, 0); PG8_LDB(B1, 0, 1); PG8_SCHED; PG8_LDA(At, 0, 0); PG8_STAGE(PG8_SA(1, 1), a1 + hstepA, voffA);
;             PG8_WAIT_V(8); PG8_WAIT_L(0); PG8_BAR; PG8_MMA(0, 0, At, B0); PG8_MMA(0, 1, At, B1); PG8_BAR; PG8_SCHED;
;             PG8_LDA(At, 0, 1); PG8_STAGE(PG8_SB(0, 0), b2, voffB); PG8_STAGE(PG8_SB(0, 1), b2 + hstep, voffB); PG8_STAGE(PG8_SA(0, 0), a2, voffA);
;             PG8_WAIT_V(8); PG8_WAIT_L(0); PG8_BAR; PG8_MMA(1, 0, At, B0); PG8_MMA(1, 1, At, B1); PG8_BAR; PG8_SCHED;
.LBB0_488:
	s_add_u32 s6, s4, 0x100
	s_addc_u32 s7, s5, 0
	s_add_i32 s24, 0, 0x10000
	s_cmp_eq_u32 s80, 44
	s_cselect_b32 s53, s43, s7
	s_cselect_b32 s52, s42, s6
	s_cselect_b32 s51, s49, s79
	s_cselect_b32 s50, s48, s78
	s_add_i32 s25, 0, 0x14000
	v_add_u32_e32 v142, s24, v186
	v_add_u32_e32 v168, s25, v186
	ds_read_b128 v[130:133], v142
	ds_read_b128 v[134:137], v142 offset:1024
	ds_read_b128 v[138:141], v142 offset:2048
	ds_read_b128 v[142:145], v142 offset:3072
	ds_read_b128 v[146:149], v168
	ds_read_b128 v[150:153], v168 offset:1024
	ds_read_b128 v[164:167], v168 offset:2048
	ds_read_b128 v[180:183], v168 offset:3072
	v_lshl_add_u64 v[168:169], s[4:5], 0, v[160:161]
	s_add_i32 m0, s15, 0xc000
	ds_read_b128 v[190:193], v188
	ds_read_b128 v[194:197], v188 offset:1024
	ds_read_b128 v[198:201], v188 offset:2048
	ds_read_b128 v[202:205], v188 offset:3072
	ds_read_b128 v[206:209], v188 offset:4096
	ds_read_b128 v[230:233], v188 offset:5120
	ds_read_b128 v[234:237], v188 offset:6144
	ds_read_b128 v[238:241], v188 offset:7168
	global_load_lds_dwordx4 v[168:169], off
	v_lshl_add_u64 v[168:169], s[4:5], 0, v[162:163]
	s_add_i32 m0, s15, 0xe000
	s_nop 0
	global_load_lds_dwordx4 v[168:169], off
	s_waitcnt vmcnt(8)
	s_waitcnt lgkmcnt(0)
	s_barrier
	s_setprio 1
	v_mfma_f32_16x16x32_bf16 v[126:129], v[130:133], v[190:193], v[126:129]
	v_mfma_f32_16x16x32_bf16 v[122:125], v[138:141], v[190:193], v[122:125]
	v_mfma_f32_16x16x32_bf16 v[110:113], v[130:133], v[198:201], v[110:113]
	v_mfma_f32_16x16x32_bf16 v[106:109], v[138:141], v[198:201], v[106:109]
	v_mfma_f32_16x16x32_bf16 v[98:101], v[130:133], v[206:209], v[98:101]
	v_mfma_f32_16x16x32_bf16 v[90:93], v[138:141], v[206:209], v[90:93]
	v_mfma_f32_16x16x32_bf16 v[82:85], v[130:133], v[234:237], v[82:85]
	v_mfma_f32_16x16x32_bf16 v[74:77], v[138:141], v[234:237], v[74:77]
	v_mfma_f32_16x16x32_bf16 v[126:129], v[134:137], v[194:197], v[126:129]
	v_mfma_f32_16x16x32_bf16 v[122:125], v[142:145], v[194:197], v[122:125]
	v_mfma_f32_16x16x32_bf16 v[110:113], v[134:137], v[202:205], v[110:113]
	v_mfma_f32_16x16x32_bf16 v[106:109], v[142:145], v[202:205], v[106:109]
	v_mfma_f32_16x16x32_bf16 v[98:101], v[134:137], v[230:233], v[98:101]
	v_mfma_f32_16x16x32_bf16 v[90:93], v[142:145], v[230:233], v[90:93]
	v_mfma_f32_16x16x32_bf16 v[82:85], v[134:137], v[238:241], v[82:85]
	v_mfma_f32_16x16x32_bf16 v[74:77], v[142:145], v[238:241], v[74:77]
	v_mfma_f32_16x16x32_bf16 v[118:121], v[146:149], v[190:193], v[118:121]
	v_mfma_f32_16x16x32_bf16 v[114:117], v[164:167], v[190:193], v[114:117]
	v_mfma_f32_16x16x32_bf16 v[102:105], v[146:149], v[198:201], v[102:105]
	v_mfma_f32_16x16x32_bf16 v[94:97], v[164:167], v[198:201], v[94:97]
	v_mfma_f32_16x16x32_bf16 v[86:89], v[146:149], v[206:209], v[86:89]
	v_mfma_f32_16x16x32_bf16 v[78:81], v[164:167], v[206:209], v[78:81]
	v_mfma_f32_16x16x32_bf16 v[70:73], v[146:149], v[234:237], v[70:73]
	v_mfma_f32_16x16x32_bf16 v[66:69], v[164:167], v[234:237], v[66:69]
	v_mfma_f32_16x16x32_bf16 v[118:121], v[150:153], v[194:197], v[118:121]
	v_mfma_f32_16x16x32_bf16 v[114:117], v[180:183], v[194:197], v[114:117]
	v_mfma_f32_16x16x32_bf16 v[102:105], v[150:153], v[202:205], v[102:105]
	v_mfma_f32_16x16x32_bf16 v[94:97], v[180:183], v[202:205], v[94:97]
	v_mfma_f32_16x16x32_bf16 v[86:89], v[150:153], v[230:233], v[86:89]
	v_mfma_f32_16x16x32_bf16 v[78:81], v[180:183], v[230:233], v[78:81]
	v_mfma_f32_16x16x32_bf16 v[70:73], v[150:153], v[238:241], v[70:73]
	v_mfma_f32_16x16x32_bf16 v[66:69], v[180:183], v[238:241], v[66:69]
	s_setprio 0
	s_barrier
	s_add_i32 s4, s24, s13
	v_lshl_add_u64 v[168:169], s[50:51], 0, v[0:1]
	s_mov_b32 m0, s4
	ds_read_b128 v[190:193], v188 offset:16384
	ds_read_b128 v[194:197], v188 offset:17408
	ds_read_b128 v[198:201], v188 offset:18432
	ds_read_b128 v[202:205], v188 offset:19456
	ds_read_b128 v[206:209], v188 offset:20480
	ds_read_b128 v[230:233], v188 offset:21504
	ds_read_b128 v[234:237], v188 offset:22528
	ds_read_b128 v[238:241], v188 offset:23552
	global_load_lds_dwordx4 v[168:169], off
	s_add_i32 m0, s4, 0x2000
	s_add_u32 s4, s50, 0xc0000
	v_lshl_add_u64 v[184:185], s[50:51], 0, v[154:155]
	s_addc_u32 s5, s51, 0
	s_add_i32 s24, s25, s13
	global_load_lds_dwordx4 v[184:185], off
	v_lshl_add_u64 v[214:215], s[4:5], 0, v[0:1]
	s_mov_b32 m0, s24
	v_lshl_add_u64 v[228:229], s[52:53], 0, v[156:157]
	global_load_lds_dwordx4 v[214:215], off
	v_lshl_add_u64 v[214:215], s[4:5], 0, v[154:155]
	s_add_i32 m0, s24, 0x2000
	s_nop 0
	global_load_lds_dwordx4 v[214:215], off
	v_lshl_add_u64 v[214:215], s[52:53], 0, v[158:159]
	s_mov_b32 m0, s15
	s_nop 0
	global_load_lds_dwordx4 v[214:215], off
	s_mov_b32 m0, s17
	s_nop 0
	global_load_lds_dwordx4 v[228:229], off
	s_waitcnt vmcnt(8)
	s_waitcnt lgkmcnt(0)
	s_barrier
; #define PG8_STAGE(bufoff, gbase, voff) do { _Pragma("unroll") for (int _i = 0; _i < 2; ++_i) \
;         __builtin_amdgcn_global_load_lds((const unsigned*)((const char*)(gbase) + (voff)[_i]), (LAS unsigned*)(lds + (bufoff) + ldsw + _i * 8192), 16, 0, 0); } while (0)
; #define PG8_LDA(dst, b, h) do { _Pragma("unroll") for (int m = 0; m < 4; ++m) _Pragma("unroll") for (int k = 0; k < 2; ++k) dst[m][k] = *(const LAS bf16x8*)(lds + PG8_SA(b, h) + aoff + m * 2048 + k * 1024); } while (0)
; #define PG8_LDB(dst, b, h) do { _Pragma("unroll") for (int n = 0; n < 2; ++n) _Pragma("unroll") for (int k = 0; k < 2; ++k) dst[n][k] = *(const LAS bf16x8*)(lds + PG8_SB(b, h) + boff + n * 2048 + k * 1024); } while (0)
; #define PG8_MMA(ai, bj, At, Bt) do { __builtin_amdgcn_s_setprio(1); _Pragma("unroll") for (int m = 0; m < 4; ++m) _Pragma("unroll") for (int n = 0; n < 2; ++n) _Pragma("unroll") for (int k = 0; k < 2; ++k) \
;         acc[ai][bj][m][n] = __builtin_amdgcn_mfma_f32_16x16x32_bf16(Bt[n][k], At[m][k], acc[ai][bj][m][n], 0, 0, 0); __builtin_amdgcn_s_setprio(0); } while (0)
; #define PG8_WAIT_V(n) asm volatile("s_waitcnt vmcnt(" #n ")" ::: "memory")
; #define PG8_WAIT_L(n) asm volatile("s_waitcnt lgkmcnt(" #n ")" ::: "memory")
; #define PG8_BAR __builtin_amdgcn_s_barrier()
; #define PG8_SCHED __builtin_amdgcn_sched_barrier(0)
; template <bool ALIGN_EPI, class Epi, class Sched>
; DEV void gemm_phase(LAS unsigned char* lds, const Gemm g, const Sched& S, const Epi& E) {
;     ...
;             PG8_WAIT_V(8); PG8_WAIT_L(0); PG8_BAR; PG8_MMA(1, 0, At, B0); PG8_MMA(1, 1, At, B1); PG8_BAR; PG8_SCHED;
;             PG8_LDB(B0, 1, 0); PG8_LDB(B1, 1, 1); PG8_SCHED; PG8_LDA(At, 1, 0); PG8_STAGE(PG8_SA(0, 1), a2 + hstepA, voffA);
;             PG8_WAIT_V(8); PG8_WAIT_L(0); PG8_BAR; PG8_MMA(0, 0, At, B0); PG8_MMA(0, 1, At, B1); PG8_BAR; PG8_SCHED;
	s_setprio 1
	v_mfma_f32_16x16x32_bf16 v[62:65], v[130:133], v[190:193], v[62:65]
	v_mfma_f32_16x16x32_bf16 v[58:61], v[138:141], v[190:193], v[58:61]
	v_mfma_f32_16x16x32_bf16 v[50:53], v[130:133], v[198:201], v[50:53]
	v_mfma_f32_16x16x32_bf16 v[42:45], v[138:141], v[198:201], v[42:45]
	v_mfma_f32_16x16x32_bf16 v[34:37], v[130:133], v[206:209], v[34:37]
	v_mfma_f32_16x16x32_bf16 v[26:29], v[138:141], v[206:209], v[26:29]
	v_mfma_f32_16x16x32_bf16 v[18:21], v[130:133], v[234:237], v[18:21]
	v_mfma_f32_16x16x32_bf16 v[10:13], v[138:141], v[234:237], v[10:13]
	v_mfma_f32_16x16x32_bf16 v[62:65], v[134:137], v[194:197], v[62:65]
	v_mfma_f32_16x16x32_bf16 v[58:61], v[142:145], v[194:197], v[58:61]
	v_mfma_f32_16x16x32_bf16 v[50:53], v[134:137], v[202:205], v[50:53]
	v_mfma_f32_16x16x32_bf16 v[42:45], v[142:145], v[202:205], v[42:45]
	v_mfma_f32_16x16x32_bf16 v[34:37], v[134:137], v[230:233], v[34:37]
	v_mfma_f32_16x16x32_bf16 v[26:29], v[142:145], v[230:233], v[26:29]
	v_mfma_f32_16x16x32_bf16 v[18:21], v[134:137], v[238:241], v[18:21]
	v_mfma_f32_16x16x32_bf16 v[10:13], v[142:145], v[238:241], v[10:13]
	v_mfma_f32_16x16x32_bf16 v[54:57], v[146:149], v[190:193], v[54:57]
	v_mfma_f32_16x16x32_bf16 v[46:49], v[164:167], v[190:193], v[46:49]
	v_mfma_f32_16x16x32_bf16 v[38:41], v[146:149], v[198:201], v[38:41]
	v_mfma_f32_16x16x32_bf16 v[30:33], v[164:167], v[198:201], v[30:33]
	v_mfma_f32_16x16x32_bf16 v[22:25], v[146:149], v[206:209], v[22:25]
	v_mfma_f32_16x16x32_bf16 v[14:17], v[164:167], v[206:209], v[14:17]
	v_mfma_f32_16x16x32_bf16 v[6:9], v[146:149], v[234:237], v[6:9]
	v_mfma_f32_16x16x32_bf16 v[2:5], v[164:167], v[234:237], v[2:5]
	v_mfma_f32_16x16x32_bf16 v[54:57], v[150:153], v[194:197], v[54:57]
	v_mfma_f32_16x16x32_bf16 v[46:49], v[180:183], v[194:197], v[46:49]
	v_mfma_f32_16x16x32_bf16 v[38:41], v[150:153], v[202:205], v[38:41]
	v_mfma_f32_16x16x32_bf16 v[30:33], v[180:183], v[202:205], v[30:33]
	v_mfma_f32_16x16x32_bf16 v[22:25], v[150:153], v[230:233], v[22:25]
	v_mfma_f32_16x16x32_bf16 v[14:17], v[180:183], v[230:233], v[14:17]
	v_mfma_f32_16x16x32_bf16 v[6:9], v[150:153], v[238:241], v[6:9]
	v_mfma_f32_16x16x32_bf16 v[2:5], v[180:183], v[238:241], v[2:5]
	s_setprio 0
	s_barrier
	s_add_i32 s24, 0, 0x18000
	s_add_i32 s25, 0, 0x1c000
	v_add_u32_e32 v142, s24, v186
	v_add_u32_e32 v180, s25, v186
	ds_read_b128 v[130:133], v142
	ds_read_b128 v[134:137], v142 offset:1024
	ds_read_b128 v[138:141], v142 offset:2048
	ds_read_b128 v[142:145], v142 offset:3072
	ds_read_b128 v[146:149], v180
	ds_read_b128 v[150:153], v180 offset:1024
	ds_read_b128 v[164:167], v180 offset:2048
	ds_read_b128 v[180:183], v180 offset:3072
	s_add_u32 s4, s52, 0xc0000
	s_addc_u32 s5, s53, 0
	s_mov_b32 m0, s20
	v_lshl_add_u64 v[242:243], s[4:5], 0, v[158:159]
	ds_read_b128 v[190:193], v188 offset:32768
	ds_read_b128 v[194:197], v188 offset:33792
	ds_read_b128 v[198:201], v188 offset:34816
	ds_read_b128 v[202:205], v188 offset:35840
	ds_read_b128 v[206:209], v188 offset:36864
	ds_read_b128 v[230:233], v188 offset:37888
	ds_read_b128 v[234:237], v188 offset:38912
	ds_read_b128 v[238:241], v188 offset:39936
	global_load_lds_dwordx4 v[242:243], off
	v_lshl_add_u64 v[242:243], s[4:5], 0, v[156:157]
	s_mov_b32 m0, s21
	s_nop 0
	global_load_lds_dwordx4 v[242:243], off
	s_waitcnt vmcnt(8)
	s_waitcnt lgkmcnt(0)
	s_barrier
	s_setprio 1
	v_mfma_f32_16x16x32_bf16 v[126:129], v[130:133], v[190:193], v[126:129]
	v_mfma_f32_16x16x32_bf16 v[122:125], v[138:141], v[190:193], v[122:125]
	v_mfma_f32_16x16x32_bf16 v[110:113], v[130:133], v[198:201], v[110:113]
	v_mfma_f32_16x16x32_bf16 v[106:109], v[138:141], v[198:201], v[106:109]
	v_mfma_f32_16x16x32_bf16 v[98:101], v[130:133], v[206:209], v[98:101]
	v_mfma_f32_16x16x32_bf16 v[90:93], v[138:141], v[206:209], v[90:93]
	v_mfma_f32_16x16x32_bf16 v[82:85], v[130:133], v[234:237], v[82:85]
	v_mfma_f32_16x16x32_bf16 v[74:77], v[138:141], v[234:237], v[74:77]
	v_mfma_f32_16x16x32_bf16 v[126:129], v[134:137], v[194:197], v[126:129]
	v_mfma_f32_16x16x32_bf16 v[122:125], v[142:145], v[194:197], v[122:125]
	v_mfma_f32_16x16x32_bf16 v[110:113], v[134:137], v[202:205], v[110:113]
	v_mfma_f32_16x16x32_bf16 v[106:109], v[142:145], v[202:205], v[106:109]
	v_mfma_f32_16x16x32_bf16 v[98:101], v[134:137], v[230:233], v[98:101]
	v_mfma_f32_16x16x32_bf16 v[90:93], v[142:145], v[230:233], v[90:93]
	v_mfma_f32_16x16x32_bf16 v[82:85], v[134:137], v[238:241], v[82:85]
	v_mfma_f32_16x16x32_bf16 v[74:77], v[142:145], v[238:241], v[74:77]
	v_mfma_f32_16x16x32_bf16 v[118:121], v[146:149], v[190:193], v[118:121]
	v_mfma_f32_16x16x32_bf16 v[114:117], v[164:167], v[190:193], v[114:117]
	v_mfma_f32_16x16x32_bf16 v[102:105], v[146:149], v[198:201], v[102:105]
	v_mfma_f32_16x16x32_bf16 v[94:97], v[164:167], v[198:201], v[94:97]
	v_mfma_f32_16x16x32_bf16 v[86:89], v[146:149], v[206:209], v[86:89]
	v_mfma_f32_16x16x32_bf16 v[78:81], v[164:167], v[206:209], v[78:81]
	v_mfma_f32_16x16x32_bf16 v[70:73], v[146:149], v[234:237], v[70:73]
	v_mfma_f32_16x16x32_bf16 v[66:69], v[164:167], v[234:237], v[66:69]
	v_mfma_f32_16x16x32_bf16 v[118:121], v[150:153], v[194:197], v[118:121]
	v_mfma_f32_16x16x32_bf16 v[114:117], v[180:183], v[194:197], v[114:117]
	v_mfma_f32_16x16x32_bf16 v[102:105], v[150:153], v[202:205], v[102:105]
	v_mfma_f32_16x16x32_bf16 v[94:97], v[180:183], v[202:205], v[94:97]
	v_mfma_f32_16x16x32_bf16 v[86:89], v[150:153], v[230:233], v[86:89]
	v_mfma_f32_16x16x32_bf16 v[78:81], v[180:183], v[230:233], v[78:81]
	v_mfma_f32_16x16x32_bf16 v[70:73], v[150:153], v[238:241], v[70:73]
	v_mfma_f32_16x16x32_bf16 v[66:69], v[180:183], v[238:241], v[66:69]
	s_setprio 0
	s_barrier
; #define PG8_STAGE(bufoff, gbase, voff) do { _Pragma("unroll") for (int _i = 0; _i < 2; ++_i) \
;         __builtin_amdgcn_global_load_lds((const unsigned*)((const char*)(gbase) + (voff)[_i]), (LAS unsigned*)(lds + (bufoff) + ldsw + _i * 8192), 16, 0, 0); } while (0)
; #define PG8_LDA(dst, b, h) do { _Pragma("unroll") for (int m = 0; m < 4; ++m) _Pragma("unroll") for (int k = 0; k < 2; ++k) dst[m][k] = *(const LAS bf16x8*)(lds + PG8_SA(b, h) + aoff + m * 2048 + k * 1024); } while (0)
; #define PG8_LDB(dst, b, h) do { _Pragma("unroll") for (int n = 0; n < 2; ++n) _Pragma("unroll") for (int k = 0; k < 2; ++k) dst[n][k] = *(const LAS bf16x8*)(lds + PG8_SB(b, h) + boff + n * 2048 + k * 1024); } while (0)
; #define PG8_WAIT_V(n) asm volatile("s_waitcnt vmcnt(" #n ")" ::: "memory")
; #define PG8_WAIT_L(n) asm volatile("s_waitcnt lgkmcnt(" #n ")" ::: "memory")
; template <bool ALIGN_EPI, class Epi, class Sched>
; DEV void gemm_phase(LAS unsigned char* lds, const Gemm g, const Sched& S, const Epi& E) {
;     ...
;         for (int t = 0; t < nt; t += 2) {
;             const bool last = (t == nt - 2);
;             const char* a1 = cA + (size_t)(t + 1) * kstep;
;             const char* a2 = last ? nA : cA + (size_t)(t + 2) * kstep; const char* b2 = last ? nB : cB + (size_t)(t + 2) * kstep;
;             const char* a3 = a2 + kstep; const char* b3 = b2 + kstep;
;             PG8_LDB(B0, 0, 0); PG8_LDB(B1, 0, 1); PG8_SCHED; PG8_LDA(At, 0, 0); PG8_STAGE(PG8_SA(1, 1), a1 + hstepA, voffA);
;             PG8_WAIT_V(8); PG8_WAIT_L(0); PG8_BAR; PG8_MMA(0, 0, At, B0); PG8_MMA(0, 1, At, B1); PG8_BAR; PG8_SCHED;
;             PG8_LDA(At, 0, 1); PG8_STAGE(PG8_SB(0, 0), b2, voffB); PG8_STAGE(PG8_SB(0, 1), b2 + hstep, voffB); PG8_STAGE(PG8_SA(0, 0), a2, voffA);
;             PG8_WAIT_V(8); PG8_WAIT_L(0); PG8_BAR; PG8_MMA(1, 0, At, B0); PG8_MMA(1, 1, At, B1); PG8_BAR; PG8_SCHED;
;             PG8_LDB(B0, 1, 0); PG8_LDB(B1, 1, 1); PG8_SCHED; PG8_LDA(At, 1, 0); PG8_STAGE(PG8_SA(0, 1), a2 + hstepA, voffA);
;             PG8_WAIT_V(8); PG8_WAIT_L(0); PG8_BAR; PG8_MMA(0, 0, At, B0); PG8_MMA(0, 1, At, B1); PG8_BAR; PG8_SCHED;
;             PG8_LDA(At, 1, 1); PG8_STAGE(PG8_SB(1, 0), b3, voffB); PG8_STAGE(PG8_SB(1, 1), b3 + hstep, voffB); PG8_STAGE(PG8_SA(1, 0), a3, voffA);
;             PG8_WAIT_V(8); PG8_WAIT_L(0); PG8_BAR; PG8_MMA(1, 0, At, B0); PG8_MMA(1, 1, At, B1); PG8_BAR; PG8_SCHED;
	s_add_i32 s4, s24, s13
	v_lshl_add_u64 v[168:169], v[168:169], 0, s[30:31]
	s_mov_b32 m0, s4
	ds_read_b128 v[190:193], v188 offset:49152
	ds_read_b128 v[194:197], v188 offset:50176
	ds_read_b128 v[198:201], v188 offset:51200
	ds_read_b128 v[202:205], v188 offset:52224
	ds_read_b128 v[206:209], v188 offset:53248
	ds_read_b128 v[230:233], v188 offset:54272
	ds_read_b128 v[234:237], v188 offset:55296
	ds_read_b128 v[238:241], v188 offset:56320
	global_load_lds_dwordx4 v[168:169], off
	s_add_i32 m0, s4, 0x2000
	s_add_u32 s4, s50, 0xc0080
	v_lshl_add_u64 v[168:169], v[184:185], 0, s[30:31]
	s_addc_u32 s5, s51, 0
	s_add_i32 s24, s25, s13
	global_load_lds_dwordx4 v[168:169], off
	v_lshl_add_u64 v[168:169], s[4:5], 0, v[0:1]
	s_mov_b32 m0, s24
	s_nop 0
	global_load_lds_dwordx4 v[168:169], off
	v_lshl_add_u64 v[168:169], s[4:5], 0, v[154:155]
	s_add_i32 m0, s24, 0x2000
	s_nop 0
	global_load_lds_dwordx4 v[168:169], off
	v_lshl_add_u64 v[168:169], v[214:215], 0, s[30:31]
	s_mov_b32 m0, s36
	s_nop 0
	global_load_lds_dwordx4 v[168:169], off
	v_lshl_add_u64 v[168:169], v[228:229], 0, s[30:31]
	s_mov_b32 m0, s54
	s_nop 0
	global_load_lds_dwordx4 v[168:169], off
	s_waitcnt vmcnt(8)
	s_waitcnt lgkmcnt(0)
	s_barrier
	s_setprio 1
	v_mfma_f32_16x16x32_bf16 v[62:65], v[130:133], v[190:193], v[62:65]
	v_mfma_f32_16x16x32_bf16 v[58:61], v[138:141], v[190:193], v[58:61]
	v_mfma_f32_16x16x32_bf16 v[50:53], v[130:133], v[198:201], v[50:53]
	v_mfma_f32_16x16x32_bf16 v[42:45], v[138:141], v[198:201], v[42:45]
	v_mfma_f32_16x16x32_bf16 v[34:37], v[130:133], v[206:209], v[34:37]
	v_mfma_f32_16x16x32_bf16 v[26:29], v[138:141], v[206:209], v[26:29]
	v_mfma_f32_16x16x32_bf16 v[18:21], v[130:133], v[234:237], v[18:21]
	v_mfma_f32_16x16x32_bf16 v[10:13], v[138:141], v[234:237], v[10:13]
	v_mfma_f32_16x16x32_bf16 v[62:65], v[134:137], v[194:197], v[62:65]
	v_mfma_f32_16x16x32_bf16 v[58:61], v[142:145], v[194:197], v[58:61]
	v_mfma_f32_16x16x32_bf16 v[50:53], v[134:137], v[202:205], v[50:53]
	v_mfma_f32_16x16x32_bf16 v[42:45], v[142:145], v[202:205], v[42:45]
	v_mfma_f32_16x16x32_bf16 v[34:37], v[134:137], v[230:233], v[34:37]
	v_mfma_f32_16x16x32_bf16 v[26:29], v[142:145], v[230:233], v[26:29]
	v_mfma_f32_16x16x32_bf16 v[18:21], v[134:137], v[238:241], v[18:21]
	v_mfma_f32_16x16x32_bf16 v[10:13], v[142:145], v[238:241], v[10:13]
	v_mfma_f32_16x16x32_bf16 v[54:57], v[146:149], v[190:193], v[54:57]
	v_mfma_f32_16x16x32_bf16 v[46:49], v[164:167], v[190:193], v[46:49]
	v_mfma_f32_16x16x32_bf16 v[38:41], v[146:149], v[198:201], v[38:41]
	v_mfma_f32_16x16x32_bf16 v[30:33], v[164:167], v[198:201], v[30:33]
	v_mfma_f32_16x16x32_bf16 v[22:25], v[146:149], v[206:209], v[22:25]
	v_mfma_f32_16x16x32_bf16 v[14:17], v[164:167], v[206:209], v[14:17]
	v_mfma_f32_16x16x32_bf16 v[6:9], v[146:149], v[234:237], v[6:9]
	v_mfma_f32_16x16x32_bf16 v[2:5], v[164:167], v[234:237], v[2:5]
	v_mfma_f32_16x16x32_bf16 v[54:57], v[150:153], v[194:197], v[54:57]
	v_mfma_f32_16x16x32_bf16 v[46:49], v[180:183], v[194:197], v[46:49]
	v_mfma_f32_16x16x32_bf16 v[38:41], v[150:153], v[202:205], v[38:41]
	v_mfma_f32_16x16x32_bf16 v[30:33], v[180:183], v[202:205], v[30:33]
	v_mfma_f32_16x16x32_bf16 v[22:25], v[150:153], v[230:233], v[22:25]
	v_mfma_f32_16x16x32_bf16 v[14:17], v[180:183], v[230:233], v[14:17]
	v_mfma_f32_16x16x32_bf16 v[6:9], v[150:153], v[238:241], v[6:9]
	v_mfma_f32_16x16x32_bf16 v[2:5], v[180:183], v[238:241], v[2:5]
	s_setprio 0
	s_barrier
	s_add_i32 s80, s80, 2
	s_add_u32 s78, s78, 0x100
	s_addc_u32 s79, s79, 0
	s_cmp_gt_u32 s80, 45
	s_mov_b64 s[4:5], s[6:7]
	s_cbranch_scc0 .LBB0_488
	s_and_b64 vcc, exec, s[46:47]
	s_cbranch_vccz .LBB0_491
	s_barrier
